# gdn_prep forward substitution: removed the s_nop 0 pads between dependent inline-asm v_fma_f32 (no hazard between plain VALU ops)
# speedup vs baseline: 1.1009x; 1.1009x over previous
.LBB0_514:
	s_or_b64 exec, exec, s[56:57]
	v_mov_b32 v2, 0
	v_cmp_gt_i32_e32 vcc, s75, v102
	v_lshlrev_b32_e32 v2, 2, v2
	v_and_b32_e32 v4, 0x7f, v102
	v_cndmask_b32_e32 v3, v167, v164, vcc
	v_add_u32_e32 v62, v3, v2
	v_cndmask_b32_e32 v3, v163, v168, vcc
	v_lshl_add_u32 v63, v4, 1, v3
	ds_read_u16 v3, v63
	ds_read_b32 v4, v62
	v_add_u32_e32 v24, v143, v2
	v_add_u32_e32 v57, 0xf400, v24
	s_waitcnt lgkmcnt(1)
	v_lshlrev_b32_e32 v2, 16, v3
	s_waitcnt lgkmcnt(0)
	v_mul_f32_e32 v45, v4, v2
	ds_read_u16 v6, v63 offset:272
	ds_read_b32 v7, v62 offset:4
	ds_read_b128 v[2:5], v24 offset:62736
	s_waitcnt lgkmcnt(0)
	v_lshlrev_b32_e32 v3, 16, v6
	v_mul_f32_e32 v46, v7, v3
	ds_read_u16 v3, v63 offset:544
	ds_read_b32 v8, v62 offset:8
	ds_read_b128 v[4:7], v24 offset:63008
	v_fma_f32 v46, -v2, v45, v46
	s_waitcnt lgkmcnt(2)
	v_lshlrev_b32_e32 v3, 16, v3
	s_waitcnt lgkmcnt(1)
	v_mul_f32_e32 v47, v8, v3
	ds_read_u16 v2, v63 offset:816
	ds_read_b32 v3, v62 offset:12
	s_waitcnt lgkmcnt(2)
	ds_read_b128 v[6:9], v24 offset:63280
	v_fma_f32 v47, -v4, v45, v47
	s_waitcnt lgkmcnt(2)
	v_lshlrev_b32_e32 v2, 16, v2
	s_waitcnt lgkmcnt(1)
	v_mul_f32_e32 v48, v3, v2
	v_fma_f32 v47, -v5, v46, v47
	s_waitcnt lgkmcnt(0)
	ds_read_u16 v9, v63 offset:1088
	ds_read_b32 v10, v62 offset:16
	ds_read_b128 v[2:5], v24 offset:63552
	v_fma_f32 v48, -v6, v45, v48
	s_waitcnt lgkmcnt(2)
	v_lshlrev_b32_e32 v6, 16, v9
	v_fma_f32 v48, -v7, v46, v48
	s_waitcnt lgkmcnt(1)
	v_mul_f32_e32 v49, v10, v6
	v_fma_f32 v48, -v8, v47, v48
	ds_read_u16 v14, v63 offset:1360
	ds_read_b32 v15, v62 offset:20
	ds_read_b128 v[6:9], v24 offset:63824
	ds_read_b128 v[10:13], v24 offset:63840
	s_waitcnt lgkmcnt(4)
	v_fma_f32 v49, -v2, v45, v49
	s_waitcnt lgkmcnt(3)
	v_lshlrev_b32_e32 v2, 16, v14
	v_fma_f32 v49, -v3, v46, v49
	s_waitcnt lgkmcnt(2)
	v_mul_f32_e32 v50, v15, v2
	v_fma_f32 v49, -v4, v47, v49
	v_fma_f32 v49, -v5, v48, v49
	s_waitcnt lgkmcnt(0)
	ds_read_u16 v11, v63 offset:1632
	ds_read_b32 v16, v62 offset:24
	ds_read_b128 v[2:5], v24 offset:64096
	ds_read_b128 v[12:15], v24 offset:64112
	v_fma_f32 v50, -v6, v45, v50
	s_waitcnt lgkmcnt(3)
	v_lshlrev_b32_e32 v6, 16, v11
	v_fma_f32 v50, -v7, v46, v50
	s_waitcnt lgkmcnt(2)
	v_mul_f32_e32 v51, v16, v6
	v_fma_f32 v50, -v8, v47, v50
	v_fma_f32 v50, -v9, v48, v50
	v_fma_f32 v50, -v10, v49, v50
	s_waitcnt lgkmcnt(1)
	v_fma_f32 v51, -v2, v45, v51
	ds_read_u16 v10, v63 offset:1904
	ds_read_b32 v11, v62 offset:28
	ds_read_b128 v[6:9], v24 offset:64368
	s_waitcnt lgkmcnt(3)
	ds_read_b128 v[14:17], v24 offset:64384
	v_fma_f32 v51, -v3, v46, v51
	s_waitcnt lgkmcnt(3)
	v_lshlrev_b32_e32 v2, 16, v10
	v_fma_f32 v51, -v4, v47, v51
	s_waitcnt lgkmcnt(2)
	v_mul_f32_e32 v52, v11, v2
	v_fma_f32 v51, -v5, v48, v51
	v_fma_f32 v51, -v12, v49, v51
	v_fma_f32 v51, -v13, v50, v51
	s_waitcnt lgkmcnt(1)
	v_fma_f32 v52, -v6, v45, v52
	s_waitcnt lgkmcnt(0)
	ds_read_u16 v17, v63 offset:2176
	ds_read_b32 v18, v62 offset:32
	ds_read_b128 v[2:5], v24 offset:64640
	ds_read_b128 v[10:13], v24 offset:64656
	v_fma_f32 v52, -v7, v46, v52
	s_waitcnt lgkmcnt(3)
	v_lshlrev_b32_e32 v6, 16, v17
	v_fma_f32 v52, -v8, v47, v52
	s_waitcnt lgkmcnt(2)
	v_mul_f32_e32 v53, v18, v6
	v_fma_f32 v52, -v9, v48, v52
	v_fma_f32 v52, -v14, v49, v52
	v_fma_f32 v52, -v15, v50, v52
	v_fma_f32 v52, -v16, v51, v52
	s_waitcnt lgkmcnt(1)
	v_fma_f32 v53, -v2, v45, v53
	ds_read_u16 v22, v63 offset:2448
	ds_read_b32 v23, v62 offset:36
	ds_read_b128 v[6:9], v24 offset:64912
	ds_read_b128 v[14:17], v24 offset:64928
	ds_read_b128 v[18:21], v24 offset:64944
	v_fma_f32 v53, -v3, v46, v53
	s_waitcnt lgkmcnt(0)
	v_lshlrev_b32_e32 v19, 16, v22
	v_fma_f32 v53, -v4, v47, v53
	v_mul_f32_e32 v54, v23, v19
	v_fma_f32 v53, -v5, v48, v53
	v_fma_f32 v53, -v10, v49, v53
	v_fma_f32 v53, -v11, v50, v53
	v_fma_f32 v53, -v12, v51, v53
	v_fma_f32 v53, -v13, v52, v53
	v_fma_f32 v54, -v6, v45, v54
	ds_read_u16 v19, v63 offset:2720
	ds_read_b32 v25, v62 offset:40
	ds_read_b128 v[2:5], v24 offset:65184
	ds_read_b128 v[10:13], v24 offset:65200
	ds_read_b128 v[20:23], v24 offset:65216
	v_fma_f32 v54, -v7, v46, v54
	s_waitcnt lgkmcnt(4)
	v_lshlrev_b32_e32 v19, 16, v19
	v_fma_f32 v54, -v8, v47, v54
	s_waitcnt lgkmcnt(3)
	v_mul_f32_e32 v55, v25, v19
	v_fma_f32 v54, -v9, v48, v54
	v_fma_f32 v54, -v14, v49, v54
	v_fma_f32 v54, -v15, v50, v54
	v_fma_f32 v54, -v16, v51, v54
	v_fma_f32 v54, -v17, v52, v54
	v_fma_f32 v54, -v18, v53, v54
	s_waitcnt lgkmcnt(2)
	v_fma_f32 v55, -v2, v45, v55
	ds_read_u16 v18, v63 offset:2992
	ds_read_b32 v19, v62 offset:44
	ds_read_b128 v[6:9], v24 offset:65456
	ds_read_b128 v[14:17], v24 offset:65472
	s_waitcnt lgkmcnt(4)
	ds_read_b128 v[22:25], v24 offset:65488
	v_fma_f32 v55, -v3, v46, v55
	s_waitcnt lgkmcnt(4)
	v_lshlrev_b32_e32 v18, 16, v18
	v_fma_f32 v55, -v4, v47, v55
	s_waitcnt lgkmcnt(3)
	v_mul_f32_e32 v56, v19, v18
	v_fma_f32 v55, -v5, v48, v55
	v_fma_f32 v55, -v10, v49, v55
	v_fma_f32 v55, -v11, v50, v55
	v_fma_f32 v55, -v12, v51, v55
	v_fma_f32 v55, -v13, v52, v55
	v_fma_f32 v55, -v20, v53, v55
	v_fma_f32 v55, -v21, v54, v55
	s_waitcnt lgkmcnt(2)
	v_fma_f32 v56, -v6, v45, v56
	s_waitcnt lgkmcnt(0)
	ds_read_u16 v25, v63 offset:3264
	ds_read_b32 v26, v62 offset:48
	ds_read_b128 v[2:5], v57 offset:3264
	ds_read_b128 v[10:13], v57 offset:3280
	ds_read_b128 v[18:21], v57 offset:3296
	v_fma_f32 v56, -v7, v46, v56
	s_waitcnt lgkmcnt(4)
	v_lshlrev_b32_e32 v25, 16, v25
	v_fma_f32 v56, -v8, v47, v56
	s_waitcnt lgkmcnt(3)
	v_mul_f32_e32 v58, v26, v25
	v_fma_f32 v56, -v9, v48, v56
	v_fma_f32 v56, -v14, v49, v56
	v_fma_f32 v56, -v15, v50, v56
	v_fma_f32 v56, -v16, v51, v56
	v_fma_f32 v56, -v17, v52, v56
	v_fma_f32 v56, -v22, v53, v56
	v_fma_f32 v56, -v23, v54, v56
	v_fma_f32 v56, -v24, v55, v56
	s_waitcnt lgkmcnt(2)
	v_fma_f32 v58, -v2, v45, v58
	ds_read_u16 v22, v63 offset:3536
	ds_read_b32 v23, v62 offset:52
	ds_read_b128 v[6:9], v57 offset:3536
	ds_read_b128 v[14:17], v57 offset:3552
	v_fma_f32 v58, -v3, v46, v58
	s_waitcnt lgkmcnt(3)
	v_lshlrev_b32_e32 v22, 16, v22
	v_fma_f32 v58, -v4, v47, v58
	s_waitcnt lgkmcnt(2)
	v_mul_f32_e32 v59, v23, v22
	v_fma_f32 v58, -v5, v48, v58
	ds_read_b128 v[22:25], v57 offset:3568
	ds_read_b128 v[26:29], v57 offset:3584
	v_fma_f32 v58, -v10, v49, v58
	v_fma_f32 v58, -v11, v50, v58
	v_fma_f32 v58, -v12, v51, v58
	v_fma_f32 v58, -v13, v52, v58
	v_fma_f32 v58, -v18, v53, v58
	v_fma_f32 v58, -v19, v54, v58
	v_fma_f32 v58, -v20, v55, v58
	v_fma_f32 v58, -v21, v56, v58
	s_waitcnt lgkmcnt(3)
	v_fma_f32 v59, -v6, v45, v59
	ds_read_u16 v18, v63 offset:3808
	ds_read_b32 v19, v62 offset:56
	ds_read_b128 v[2:5], v57 offset:3808
	ds_read_b128 v[10:13], v57 offset:3824
	v_fma_f32 v59, -v7, v46, v59
	s_waitcnt lgkmcnt(3)
	v_lshlrev_b32_e32 v18, 16, v18
	v_fma_f32 v59, -v8, v47, v59
	s_waitcnt lgkmcnt(2)
	v_mul_f32_e32 v60, v19, v18
	v_fma_f32 v59, -v9, v48, v59
	ds_read_b128 v[18:21], v57 offset:3840
	ds_read_b128 v[28:31], v57 offset:3856
	v_fma_f32 v59, -v14, v49, v59
	v_fma_f32 v59, -v15, v50, v59
	v_fma_f32 v59, -v16, v51, v59
	v_fma_f32 v59, -v17, v52, v59
	v_fma_f32 v59, -v22, v53, v59
	v_fma_f32 v59, -v23, v54, v59
	v_fma_f32 v59, -v24, v55, v59
	v_fma_f32 v59, -v25, v56, v59
	v_fma_f32 v59, -v26, v58, v59
	s_waitcnt lgkmcnt(3)
	v_fma_f32 v60, -v2, v45, v60
	ds_read_u16 v22, v63 offset:4080
	ds_read_b32 v23, v62 offset:60
	ds_read_b128 v[6:9], v57 offset:4080
	ds_read_b128 v[14:17], v57 offset:4096
	v_fma_f32 v60, -v3, v46, v60
	s_waitcnt lgkmcnt(3)
	v_lshlrev_b32_e32 v22, 16, v22
	v_fma_f32 v60, -v4, v47, v60
	s_waitcnt lgkmcnt(2)
	v_mul_f32_e32 v61, v23, v22
	v_fma_f32 v60, -v5, v48, v60
	ds_read_b128 v[22:25], v57 offset:4112
	ds_read_b128 v[30:33], v57 offset:4128
	v_fma_f32 v60, -v10, v49, v60
	v_fma_f32 v60, -v11, v50, v60
	v_fma_f32 v60, -v12, v51, v60
	v_fma_f32 v60, -v13, v52, v60
	v_fma_f32 v60, -v18, v53, v60
	v_fma_f32 v60, -v19, v54, v60
	v_fma_f32 v60, -v20, v55, v60
	v_fma_f32 v60, -v21, v56, v60
	v_fma_f32 v60, -v28, v58, v60
	v_fma_f32 v60, -v29, v59, v60
	s_waitcnt lgkmcnt(3)
	v_fma_f32 v61, -v6, v45, v61
	ds_read_u16 v18, v63 offset:4352
	ds_read_b32 v19, v62 offset:64
	ds_read_b128 v[2:5], v57 offset:4352
	ds_read_b128 v[10:13], v57 offset:4368
	v_fma_f32 v61, -v7, v46, v61
	s_waitcnt lgkmcnt(3)
	v_lshlrev_b32_e32 v18, 16, v18
	v_fma_f32 v61, -v8, v47, v61
	s_waitcnt lgkmcnt(2)
	v_mul_f32_e32 v64, v19, v18
	v_fma_f32 v61, -v9, v48, v61
	ds_read_b128 v[18:21], v57 offset:4384
	ds_read_b128 v[26:29], v57 offset:4400
	v_fma_f32 v61, -v14, v49, v61
	v_fma_f32 v61, -v15, v50, v61
	v_fma_f32 v61, -v16, v51, v61
	v_fma_f32 v61, -v17, v52, v61
	v_fma_f32 v61, -v22, v53, v61
	v_fma_f32 v61, -v23, v54, v61
	v_fma_f32 v61, -v24, v55, v61
	v_fma_f32 v61, -v25, v56, v61
	v_fma_f32 v61, -v30, v58, v61
	v_fma_f32 v61, -v31, v59, v61
	v_fma_f32 v61, -v32, v60, v61
	s_waitcnt lgkmcnt(3)
	v_fma_f32 v64, -v2, v45, v64
	ds_read_u16 v22, v63 offset:4624
	ds_read_b32 v23, v62 offset:68
	ds_read_b128 v[6:9], v57 offset:4624
	ds_read_b128 v[14:17], v57 offset:4640
	v_fma_f32 v64, -v3, v46, v64
	s_waitcnt lgkmcnt(3)
	v_lshlrev_b32_e32 v22, 16, v22
	v_fma_f32 v64, -v4, v47, v64
	s_waitcnt lgkmcnt(2)
	v_mul_f32_e32 v65, v23, v22
	v_fma_f32 v64, -v5, v48, v64
	ds_read_b128 v[22:25], v57 offset:4656
	ds_read_b128 v[30:33], v57 offset:4672
	ds_read_b128 v[34:37], v57 offset:4688
	v_fma_f32 v64, -v10, v49, v64
	v_fma_f32 v64, -v11, v50, v64
	v_fma_f32 v64, -v12, v51, v64
	v_fma_f32 v64, -v13, v52, v64
	v_fma_f32 v64, -v18, v53, v64
	v_fma_f32 v64, -v19, v54, v64
	v_fma_f32 v64, -v20, v55, v64
	v_fma_f32 v64, -v21, v56, v64
	v_fma_f32 v64, -v26, v58, v64
	v_fma_f32 v64, -v27, v59, v64
	v_fma_f32 v64, -v28, v60, v64
	v_fma_f32 v64, -v29, v61, v64
	s_waitcnt lgkmcnt(4)
	v_fma_f32 v65, -v6, v45, v65
	ds_read_u16 v18, v63 offset:4896
	ds_read_b32 v19, v62 offset:72
	ds_read_b128 v[2:5], v57 offset:4896
	ds_read_b128 v[10:13], v57 offset:4912
	v_fma_f32 v65, -v7, v46, v65
	s_waitcnt lgkmcnt(3)
	v_lshlrev_b32_e32 v18, 16, v18
	v_fma_f32 v65, -v8, v47, v65
	s_waitcnt lgkmcnt(2)
	v_mul_f32_e32 v66, v19, v18
	v_fma_f32 v65, -v9, v48, v65
	ds_read_b128 v[18:21], v57 offset:4928
	ds_read_b128 v[26:29], v57 offset:4944
	ds_read_b128 v[36:39], v57 offset:4960
	v_fma_f32 v65, -v14, v49, v65
	v_fma_f32 v65, -v15, v50, v65
	v_fma_f32 v65, -v16, v51, v65
	v_fma_f32 v65, -v17, v52, v65
	v_fma_f32 v65, -v22, v53, v65
	v_fma_f32 v65, -v23, v54, v65
	v_fma_f32 v65, -v24, v55, v65
	v_fma_f32 v65, -v25, v56, v65
	v_fma_f32 v65, -v30, v58, v65
	v_fma_f32 v65, -v31, v59, v65
	v_fma_f32 v65, -v32, v60, v65
	v_fma_f32 v65, -v33, v61, v65
	v_fma_f32 v65, -v34, v64, v65
	s_waitcnt lgkmcnt(4)
	v_fma_f32 v66, -v2, v45, v66
	ds_read_u16 v22, v63 offset:5168
	ds_read_b32 v23, v62 offset:76
	ds_read_b128 v[6:9], v57 offset:5168
	ds_read_b128 v[14:17], v57 offset:5184
	v_fma_f32 v66, -v3, v46, v66
	s_waitcnt lgkmcnt(3)
	v_lshlrev_b32_e32 v22, 16, v22
	v_fma_f32 v66, -v4, v47, v66
	s_waitcnt lgkmcnt(2)
	v_mul_f32_e32 v67, v23, v22
	v_fma_f32 v66, -v5, v48, v66
	ds_read_b128 v[22:25], v57 offset:5200
	ds_read_b128 v[30:33], v57 offset:5216
	ds_read_b128 v[38:41], v57 offset:5232
	v_fma_f32 v66, -v10, v49, v66
	v_fma_f32 v66, -v11, v50, v66
	v_fma_f32 v66, -v12, v51, v66
	v_fma_f32 v66, -v13, v52, v66
	v_fma_f32 v66, -v18, v53, v66
	v_fma_f32 v66, -v19, v54, v66
	v_fma_f32 v66, -v20, v55, v66
	v_fma_f32 v66, -v21, v56, v66
	v_fma_f32 v66, -v26, v58, v66
	v_fma_f32 v66, -v27, v59, v66
	v_fma_f32 v66, -v28, v60, v66
	v_fma_f32 v66, -v29, v61, v66
	v_fma_f32 v66, -v36, v64, v66
	v_fma_f32 v66, -v37, v65, v66
	s_waitcnt lgkmcnt(4)
	v_fma_f32 v67, -v6, v45, v67
	ds_read_u16 v18, v63 offset:5440
	ds_read_b32 v19, v62 offset:80
	ds_read_b128 v[2:5], v57 offset:5440
	ds_read_b128 v[10:13], v57 offset:5456
	v_fma_f32 v67, -v7, v46, v67
	s_waitcnt lgkmcnt(3)
	v_lshlrev_b32_e32 v18, 16, v18
	v_fma_f32 v67, -v8, v47, v67
	s_waitcnt lgkmcnt(2)
	v_mul_f32_e32 v68, v19, v18
	v_fma_f32 v67, -v9, v48, v67
	ds_read_b128 v[18:21], v57 offset:5472
	ds_read_b128 v[26:29], v57 offset:5488
	ds_read_b128 v[34:37], v57 offset:5504
	v_fma_f32 v67, -v14, v49, v67
	v_fma_f32 v67, -v15, v50, v67
	v_fma_f32 v67, -v16, v51, v67
	v_fma_f32 v67, -v17, v52, v67
	v_fma_f32 v67, -v22, v53, v67
	v_fma_f32 v67, -v23, v54, v67
	v_fma_f32 v67, -v24, v55, v67
	v_fma_f32 v67, -v25, v56, v67
	v_fma_f32 v67, -v30, v58, v67
	v_fma_f32 v67, -v31, v59, v67
	v_fma_f32 v67, -v32, v60, v67
	v_fma_f32 v67, -v33, v61, v67
	v_fma_f32 v67, -v38, v64, v67
	v_fma_f32 v67, -v39, v65, v67
	v_fma_f32 v67, -v40, v66, v67
	s_waitcnt lgkmcnt(4)
	v_fma_f32 v68, -v2, v45, v68
	ds_read_u16 v22, v63 offset:5712
	ds_read_b32 v23, v62 offset:84
	ds_read_b128 v[6:9], v57 offset:5712
	ds_read_b128 v[14:17], v57 offset:5728
	v_fma_f32 v68, -v3, v46, v68
	s_waitcnt lgkmcnt(3)
	v_lshlrev_b32_e32 v22, 16, v22
	v_fma_f32 v68, -v4, v47, v68
	s_waitcnt lgkmcnt(2)
	v_mul_f32_e32 v69, v23, v22
	v_fma_f32 v68, -v5, v48, v68
	ds_read_b128 v[22:25], v57 offset:5744
	ds_read_b128 v[30:33], v57 offset:5760
	ds_read_b128 v[38:41], v57 offset:5776
	ds_read_b128 v[72:75], v57 offset:5792
	v_fma_f32 v68, -v10, v49, v68
	v_fma_f32 v68, -v11, v50, v68
	v_fma_f32 v68, -v12, v51, v68
	v_fma_f32 v68, -v13, v52, v68
	v_fma_f32 v68, -v18, v53, v68
	v_fma_f32 v68, -v19, v54, v68
	v_fma_f32 v68, -v20, v55, v68
	v_fma_f32 v68, -v21, v56, v68
	v_fma_f32 v68, -v26, v58, v68
	v_fma_f32 v68, -v27, v59, v68
	v_fma_f32 v68, -v28, v60, v68
	v_fma_f32 v68, -v29, v61, v68
	v_fma_f32 v68, -v34, v64, v68
	v_fma_f32 v68, -v35, v65, v68
	v_fma_f32 v68, -v36, v66, v68
	v_fma_f32 v68, -v37, v67, v68
	s_waitcnt lgkmcnt(5)
	v_fma_f32 v69, -v6, v45, v69
	ds_read_u16 v18, v63 offset:5984
	ds_read_b32 v19, v62 offset:88
	ds_read_b128 v[2:5], v57 offset:5984
	ds_read_b128 v[10:13], v57 offset:6000
	v_fma_f32 v69, -v7, v46, v69
	s_waitcnt lgkmcnt(3)
	v_lshlrev_b32_e32 v18, 16, v18
	v_fma_f32 v69, -v8, v47, v69
	s_waitcnt lgkmcnt(2)
	v_mul_f32_e32 v70, v19, v18
	v_fma_f32 v69, -v9, v48, v69
	ds_read_b128 v[18:21], v57 offset:6016
	ds_read_b128 v[26:29], v57 offset:6032
	ds_read_b128 v[34:37], v57 offset:6048
	ds_read_b128 v[74:77], v57 offset:6064
	v_fma_f32 v69, -v14, v49, v69
	v_fma_f32 v69, -v15, v50, v69
	v_fma_f32 v69, -v16, v51, v69
	v_fma_f32 v69, -v17, v52, v69
	v_fma_f32 v69, -v22, v53, v69
	v_fma_f32 v69, -v23, v54, v69
	v_fma_f32 v69, -v24, v55, v69
	v_fma_f32 v69, -v25, v56, v69
	v_fma_f32 v69, -v30, v58, v69
	v_fma_f32 v69, -v31, v59, v69
	v_fma_f32 v69, -v32, v60, v69
	v_fma_f32 v69, -v33, v61, v69
	v_fma_f32 v69, -v38, v64, v69
	v_fma_f32 v69, -v39, v65, v69
	v_fma_f32 v69, -v40, v66, v69
	v_fma_f32 v69, -v41, v67, v69
	v_fma_f32 v69, -v72, v68, v69
	s_waitcnt lgkmcnt(5)
	v_fma_f32 v70, -v2, v45, v70
	ds_read_u16 v22, v63 offset:6256
	ds_read_b32 v23, v62 offset:92
	ds_read_b128 v[6:9], v57 offset:6256
	ds_read_b128 v[14:17], v57 offset:6272
	v_fma_f32 v70, -v3, v46, v70
	s_waitcnt lgkmcnt(3)
	v_lshlrev_b32_e32 v22, 16, v22
	v_fma_f32 v70, -v4, v47, v70
	s_waitcnt lgkmcnt(2)
	v_mul_f32_e32 v71, v23, v22
	v_fma_f32 v70, -v5, v48, v70
	ds_read_b128 v[22:25], v57 offset:6288
	ds_read_b128 v[30:33], v57 offset:6304
	ds_read_b128 v[38:41], v57 offset:6320
	ds_read_b128 v[76:79], v57 offset:6336
	v_fma_f32 v70, -v10, v49, v70
	v_fma_f32 v70, -v11, v50, v70
	v_fma_f32 v70, -v12, v51, v70
	v_fma_f32 v70, -v13, v52, v70
	v_fma_f32 v70, -v18, v53, v70
	v_fma_f32 v70, -v19, v54, v70
	v_fma_f32 v70, -v20, v55, v70
	v_fma_f32 v70, -v21, v56, v70
	v_fma_f32 v70, -v26, v58, v70
	v_fma_f32 v70, -v27, v59, v70
	v_fma_f32 v70, -v28, v60, v70
	v_fma_f32 v70, -v29, v61, v70
	v_fma_f32 v70, -v34, v64, v70
	v_fma_f32 v70, -v35, v65, v70
	v_fma_f32 v70, -v36, v66, v70
	v_fma_f32 v70, -v37, v67, v70
	v_fma_f32 v70, -v74, v68, v70
	v_fma_f32 v70, -v75, v69, v70
	s_waitcnt lgkmcnt(5)
	v_fma_f32 v71, -v6, v45, v71
	ds_read_u16 v18, v63 offset:6528
	ds_read_b32 v19, v62 offset:96
	ds_read_b128 v[2:5], v57 offset:6528
	ds_read_b128 v[10:13], v57 offset:6544
	v_fma_f32 v71, -v7, v46, v71
	s_waitcnt lgkmcnt(3)
	v_lshlrev_b32_e32 v18, 16, v18
	v_fma_f32 v71, -v8, v47, v71
	s_waitcnt lgkmcnt(2)
	v_mul_f32_e32 v72, v19, v18
	v_fma_f32 v71, -v9, v48, v71
	ds_read_b128 v[18:21], v57 offset:6560
	ds_read_b128 v[26:29], v57 offset:6576
	ds_read_b128 v[34:37], v57 offset:6592
	ds_read_b128 v[80:83], v57 offset:6608
	v_fma_f32 v71, -v14, v49, v71
	v_fma_f32 v71, -v15, v50, v71
	v_fma_f32 v71, -v16, v51, v71
	v_fma_f32 v71, -v17, v52, v71
	v_fma_f32 v71, -v22, v53, v71
	v_fma_f32 v71, -v23, v54, v71
	v_fma_f32 v71, -v24, v55, v71
	v_fma_f32 v71, -v25, v56, v71
	v_fma_f32 v71, -v30, v58, v71
	v_fma_f32 v71, -v31, v59, v71
	v_fma_f32 v71, -v32, v60, v71
	v_fma_f32 v71, -v33, v61, v71
	v_fma_f32 v71, -v38, v64, v71
	v_fma_f32 v71, -v39, v65, v71
	v_fma_f32 v71, -v40, v66, v71
	v_fma_f32 v71, -v41, v67, v71
	v_fma_f32 v71, -v76, v68, v71
	v_fma_f32 v71, -v77, v69, v71
	v_fma_f32 v71, -v78, v70, v71
	s_waitcnt lgkmcnt(5)
	v_fma_f32 v72, -v2, v45, v72
	ds_read_u16 v22, v63 offset:6800
	ds_read_b32 v23, v62 offset:100
	ds_read_b128 v[6:9], v57 offset:6800
	ds_read_b128 v[14:17], v57 offset:6816
	v_fma_f32 v72, -v3, v46, v72
	s_waitcnt lgkmcnt(3)
	v_lshlrev_b32_e32 v22, 16, v22
	v_fma_f32 v72, -v4, v47, v72
	s_waitcnt lgkmcnt(2)
	v_mul_f32_e32 v73, v23, v22
	v_fma_f32 v72, -v5, v48, v72
	ds_read_b128 v[22:25], v57 offset:6832
	ds_read_b128 v[30:33], v57 offset:6848
	ds_read_b128 v[38:41], v57 offset:6864
	ds_read_b128 v[76:79], v57 offset:6880
	ds_read_b128 v[84:87], v57 offset:6896
	v_fma_f32 v72, -v10, v49, v72
	v_fma_f32 v72, -v11, v50, v72
	v_fma_f32 v72, -v12, v51, v72
	v_fma_f32 v72, -v13, v52, v72
	v_fma_f32 v72, -v18, v53, v72
	v_fma_f32 v72, -v19, v54, v72
	v_fma_f32 v72, -v20, v55, v72
	v_fma_f32 v72, -v21, v56, v72
	v_fma_f32 v72, -v26, v58, v72
	v_fma_f32 v72, -v27, v59, v72
	v_fma_f32 v72, -v28, v60, v72
	v_fma_f32 v72, -v29, v61, v72
	v_fma_f32 v72, -v34, v64, v72
	v_fma_f32 v72, -v35, v65, v72
	v_fma_f32 v72, -v36, v66, v72
	v_fma_f32 v72, -v37, v67, v72
	v_fma_f32 v72, -v80, v68, v72
	v_fma_f32 v72, -v81, v69, v72
	v_fma_f32 v72, -v82, v70, v72
	v_fma_f32 v72, -v83, v71, v72
	s_waitcnt lgkmcnt(6)
	v_fma_f32 v73, -v6, v45, v73
	ds_read_u16 v18, v63 offset:7072
	ds_read_b32 v19, v62 offset:104
	ds_read_b128 v[2:5], v57 offset:7072
	ds_read_b128 v[10:13], v57 offset:7088
	v_fma_f32 v73, -v7, v46, v73
	s_waitcnt lgkmcnt(3)
	v_lshlrev_b32_e32 v18, 16, v18
	v_fma_f32 v73, -v8, v47, v73
	s_waitcnt lgkmcnt(2)
	v_mul_f32_e32 v74, v19, v18
	v_fma_f32 v73, -v9, v48, v73
	ds_read_b128 v[18:21], v57 offset:7104
	ds_read_b128 v[26:29], v57 offset:7120
	ds_read_b128 v[34:37], v57 offset:7136
	ds_read_b128 v[80:83], v57 offset:7152
	ds_read_b128 v[86:89], v57 offset:7168
	v_fma_f32 v73, -v14, v49, v73
	v_fma_f32 v73, -v15, v50, v73
	v_fma_f32 v73, -v16, v51, v73
	v_fma_f32 v73, -v17, v52, v73
	v_fma_f32 v73, -v22, v53, v73
	v_fma_f32 v73, -v23, v54, v73
	v_fma_f32 v73, -v24, v55, v73
	v_fma_f32 v73, -v25, v56, v73
	v_fma_f32 v73, -v30, v58, v73
	v_fma_f32 v73, -v31, v59, v73
	v_fma_f32 v73, -v32, v60, v73
	v_fma_f32 v73, -v33, v61, v73
	v_fma_f32 v73, -v38, v64, v73
	v_fma_f32 v73, -v39, v65, v73
	v_fma_f32 v73, -v40, v66, v73
	v_fma_f32 v73, -v41, v67, v73
	v_fma_f32 v73, -v76, v68, v73
	v_fma_f32 v73, -v77, v69, v73
	v_fma_f32 v73, -v78, v70, v73
	v_fma_f32 v73, -v79, v71, v73
	v_fma_f32 v73, -v84, v72, v73
	s_waitcnt lgkmcnt(6)
	v_fma_f32 v74, -v2, v45, v74
	ds_read_u16 v22, v63 offset:7344
	ds_read_b32 v23, v62 offset:108
	ds_read_b128 v[6:9], v57 offset:7344
	ds_read_b128 v[14:17], v57 offset:7360
	v_fma_f32 v74, -v3, v46, v74
	s_waitcnt lgkmcnt(3)
	v_lshlrev_b32_e32 v22, 16, v22
	v_fma_f32 v74, -v4, v47, v74
	s_waitcnt lgkmcnt(2)
	v_mul_f32_e32 v75, v23, v22
	v_fma_f32 v74, -v5, v48, v74
	ds_read_b128 v[22:25], v57 offset:7376
	ds_read_b128 v[30:33], v57 offset:7392
	ds_read_b128 v[38:41], v57 offset:7408
	ds_read_b128 v[88:91], v57 offset:7424
	ds_read_b128 v[92:95], v57 offset:7440
	v_fma_f32 v74, -v10, v49, v74
	v_fma_f32 v74, -v11, v50, v74
	v_fma_f32 v74, -v12, v51, v74
	v_fma_f32 v74, -v13, v52, v74
	v_fma_f32 v74, -v18, v53, v74
	v_fma_f32 v74, -v19, v54, v74
	v_fma_f32 v74, -v20, v55, v74
	v_fma_f32 v74, -v21, v56, v74
	v_fma_f32 v74, -v26, v58, v74
	v_fma_f32 v74, -v27, v59, v74
	v_fma_f32 v74, -v28, v60, v74
	v_fma_f32 v74, -v29, v61, v74
	v_fma_f32 v74, -v34, v64, v74
	v_fma_f32 v74, -v35, v65, v74
	v_fma_f32 v74, -v36, v66, v74
	v_fma_f32 v74, -v37, v67, v74
	v_fma_f32 v74, -v80, v68, v74
	v_fma_f32 v74, -v81, v69, v74
	v_fma_f32 v74, -v82, v70, v74
	v_fma_f32 v74, -v83, v71, v74
	v_fma_f32 v74, -v86, v72, v74
	v_fma_f32 v74, -v87, v73, v74
	s_waitcnt lgkmcnt(6)
	v_fma_f32 v75, -v6, v45, v75
	ds_read_u16 v18, v63 offset:7616
	ds_read_b32 v19, v62 offset:112
	ds_read_b128 v[2:5], v57 offset:7616
	ds_read_b128 v[10:13], v57 offset:7632
	v_fma_f32 v75, -v7, v46, v75
	s_waitcnt lgkmcnt(3)
	v_lshlrev_b32_e32 v18, 16, v18
	v_fma_f32 v75, -v8, v47, v75
	s_waitcnt lgkmcnt(2)
	v_mul_f32_e32 v76, v19, v18
	v_fma_f32 v75, -v9, v48, v75
	ds_read_b128 v[18:21], v57 offset:7648
	ds_read_b128 v[26:29], v57 offset:7664
	ds_read_b128 v[34:37], v57 offset:7680
	ds_read_b128 v[78:81], v57 offset:7696
	ds_read_b128 v[82:85], v57 offset:7712
	v_fma_f32 v75, -v14, v49, v75
	v_fma_f32 v75, -v15, v50, v75
	v_fma_f32 v75, -v16, v51, v75
	v_fma_f32 v75, -v17, v52, v75
	v_fma_f32 v75, -v22, v53, v75
	v_fma_f32 v75, -v23, v54, v75
	v_fma_f32 v75, -v24, v55, v75
	v_fma_f32 v75, -v25, v56, v75
	v_fma_f32 v75, -v30, v58, v75
	v_fma_f32 v75, -v31, v59, v75
	v_fma_f32 v75, -v32, v60, v75
	v_fma_f32 v75, -v33, v61, v75
	v_fma_f32 v75, -v38, v64, v75
	v_fma_f32 v75, -v39, v65, v75
	v_fma_f32 v75, -v40, v66, v75
	v_fma_f32 v75, -v41, v67, v75
	v_fma_f32 v75, -v88, v68, v75
	v_fma_f32 v75, -v89, v69, v75
	v_fma_f32 v75, -v90, v70, v75
	v_fma_f32 v75, -v91, v71, v75
	v_fma_f32 v75, -v92, v72, v75
	v_fma_f32 v75, -v93, v73, v75
	v_fma_f32 v75, -v94, v74, v75
	s_waitcnt lgkmcnt(6)
	v_fma_f32 v76, -v2, v45, v76
	ds_read_u16 v22, v63 offset:7888
	ds_read_b32 v23, v62 offset:116
	ds_read_b128 v[6:9], v57 offset:7888
	ds_read_b128 v[14:17], v57 offset:7904
	v_fma_f32 v76, -v3, v46, v76
	s_waitcnt lgkmcnt(3)
	v_lshlrev_b32_e32 v22, 16, v22
	v_fma_f32 v76, -v4, v47, v76
	s_waitcnt lgkmcnt(2)
	v_mul_f32_e32 v77, v23, v22
	v_fma_f32 v76, -v5, v48, v76
	ds_read_b128 v[22:25], v57 offset:7920
	ds_read_b128 v[30:33], v57 offset:7936
	ds_read_b128 v[38:41], v57 offset:7952
	ds_read_b128 v[86:89], v57 offset:7968
	ds_read_b128 v[90:93], v57 offset:7984
	ds_read_b128 v[94:97], v57 offset:8000
	v_fma_f32 v76, -v10, v49, v76
	v_fma_f32 v76, -v11, v50, v76
	v_fma_f32 v76, -v12, v51, v76
	v_fma_f32 v76, -v13, v52, v76
	v_fma_f32 v76, -v18, v53, v76
	v_fma_f32 v76, -v19, v54, v76
	v_fma_f32 v76, -v20, v55, v76
	v_fma_f32 v76, -v21, v56, v76
	v_fma_f32 v76, -v26, v58, v76
	v_fma_f32 v76, -v27, v59, v76
	v_fma_f32 v76, -v28, v60, v76
	v_fma_f32 v76, -v29, v61, v76
	v_fma_f32 v76, -v34, v64, v76
	v_fma_f32 v76, -v35, v65, v76
	v_fma_f32 v76, -v36, v66, v76
	v_fma_f32 v76, -v37, v67, v76
	v_fma_f32 v76, -v78, v68, v76
	v_fma_f32 v76, -v79, v69, v76
	v_fma_f32 v76, -v80, v70, v76
	v_fma_f32 v76, -v81, v71, v76
	v_fma_f32 v76, -v82, v72, v76
	v_fma_f32 v76, -v83, v73, v76
	v_fma_f32 v76, -v84, v74, v76
	v_fma_f32 v76, -v85, v75, v76
	s_waitcnt lgkmcnt(7)
	v_fma_f32 v77, -v6, v45, v77
	ds_read_u16 v18, v63 offset:8160
	ds_read_b32 v19, v62 offset:120
	ds_read_b128 v[2:5], v57 offset:8160
	ds_read_b128 v[10:13], v57 offset:8176
	v_fma_f32 v77, -v7, v46, v77
	s_waitcnt lgkmcnt(3)
	v_lshlrev_b32_e32 v18, 16, v18
	v_fma_f32 v77, -v8, v47, v77
	s_waitcnt lgkmcnt(2)
	v_mul_f32_e32 v78, v19, v18
	v_fma_f32 v77, -v9, v48, v77
	ds_read_b128 v[18:21], v57 offset:8192
	ds_read_b128 v[26:29], v57 offset:8208
	ds_read_b128 v[34:37], v57 offset:8224
	ds_read_b128 v[80:83], v57 offset:8240
	ds_read_b128 v[106:109], v57 offset:8256
	ds_read_b128 v[110:113], v57 offset:8272
	v_fma_f32 v77, -v14, v49, v77
	v_fma_f32 v77, -v15, v50, v77
	v_fma_f32 v77, -v16, v51, v77
	v_fma_f32 v77, -v17, v52, v77
	v_fma_f32 v77, -v22, v53, v77
	v_fma_f32 v77, -v23, v54, v77
	v_fma_f32 v77, -v24, v55, v77
	v_fma_f32 v77, -v25, v56, v77
	v_fma_f32 v77, -v30, v58, v77
	v_fma_f32 v77, -v31, v59, v77
	v_fma_f32 v77, -v32, v60, v77
	v_fma_f32 v77, -v33, v61, v77
	v_fma_f32 v77, -v38, v64, v77
	v_fma_f32 v77, -v39, v65, v77
	v_fma_f32 v77, -v40, v66, v77
	v_fma_f32 v77, -v41, v67, v77
	v_fma_f32 v77, -v86, v68, v77
	v_fma_f32 v77, -v87, v69, v77
	v_fma_f32 v77, -v88, v70, v77
	v_fma_f32 v77, -v89, v71, v77
	v_fma_f32 v77, -v90, v72, v77
	v_fma_f32 v77, -v91, v73, v77
	v_fma_f32 v77, -v92, v74, v77
	v_fma_f32 v77, -v93, v75, v77
	v_fma_f32 v77, -v94, v76, v77
	s_waitcnt lgkmcnt(7)
	v_fma_f32 v78, -v2, v45, v78
	ds_read_u16 v22, v63 offset:8432
	ds_read_b32 v23, v62 offset:124
	ds_read_b128 v[6:9], v57 offset:8432
	ds_read_b128 v[14:17], v57 offset:8448
	v_fma_f32 v78, -v3, v46, v78
	s_waitcnt lgkmcnt(3)
	v_lshlrev_b32_e32 v22, 16, v22
	v_fma_f32 v78, -v4, v47, v78
	s_waitcnt lgkmcnt(2)
	v_mul_f32_e32 v79, v23, v22
	v_fma_f32 v78, -v5, v48, v78
	ds_read_b128 v[22:25], v57 offset:8464
	ds_read_b128 v[30:33], v57 offset:8480
	ds_read_b128 v[38:41], v57 offset:8496
	ds_read_b128 v[84:87], v57 offset:8512
	ds_read_b128 v[88:91], v57 offset:8528
	ds_read_b128 v[92:95], v57 offset:8544
	v_fma_f32 v78, -v10, v49, v78
	v_fma_f32 v78, -v11, v50, v78
	v_fma_f32 v78, -v12, v51, v78
	v_fma_f32 v78, -v13, v52, v78
	v_fma_f32 v78, -v18, v53, v78
	v_fma_f32 v78, -v19, v54, v78
	v_fma_f32 v78, -v20, v55, v78
	v_fma_f32 v78, -v21, v56, v78
	v_fma_f32 v78, -v26, v58, v78
	v_fma_f32 v78, -v27, v59, v78
	v_fma_f32 v78, -v28, v60, v78
	v_fma_f32 v78, -v29, v61, v78
	v_fma_f32 v78, -v34, v64, v78
	v_fma_f32 v78, -v35, v65, v78
	v_fma_f32 v78, -v36, v66, v78
	v_fma_f32 v78, -v37, v67, v78
	v_fma_f32 v78, -v80, v68, v78
	v_fma_f32 v78, -v81, v69, v78
	v_fma_f32 v78, -v82, v70, v78
	v_fma_f32 v78, -v83, v71, v78
	v_fma_f32 v78, -v106, v72, v78
	v_fma_f32 v78, -v107, v73, v78
	v_fma_f32 v78, -v108, v74, v78
	v_fma_f32 v78, -v109, v75, v78
	v_fma_f32 v78, -v110, v76, v78
	v_fma_f32 v78, -v111, v77, v78
	s_waitcnt lgkmcnt(7)
	v_fma_f32 v79, -v6, v45, v79
	ds_read_u16 v18, v63 offset:8704
	ds_read_b32 v19, v62 offset:128
	ds_read_b128 v[2:5], v57 offset:8704
	ds_read_b128 v[10:13], v57 offset:8720
	v_fma_f32 v79, -v7, v46, v79
	s_waitcnt lgkmcnt(3)
	v_lshlrev_b32_e32 v18, 16, v18
	v_fma_f32 v79, -v8, v47, v79
	s_waitcnt lgkmcnt(2)
	v_mul_f32_e32 v80, v19, v18
	v_fma_f32 v79, -v9, v48, v79
	ds_read_b128 v[18:21], v57 offset:8736
	ds_read_b128 v[26:29], v57 offset:8752
	ds_read_b128 v[34:37], v57 offset:8768
	ds_read_b128 v[106:109], v57 offset:8784
	ds_read_b128 v[110:113], v57 offset:8800
	ds_read_b128 v[114:117], v57 offset:8816
	v_fma_f32 v79, -v14, v49, v79
	v_fma_f32 v79, -v15, v50, v79
	v_fma_f32 v79, -v16, v51, v79
	v_fma_f32 v79, -v17, v52, v79
	v_fma_f32 v79, -v22, v53, v79
	v_fma_f32 v79, -v23, v54, v79
	v_fma_f32 v79, -v24, v55, v79
	v_fma_f32 v79, -v25, v56, v79
	v_fma_f32 v79, -v30, v58, v79
	v_fma_f32 v79, -v31, v59, v79
	v_fma_f32 v79, -v32, v60, v79
	v_fma_f32 v79, -v33, v61, v79
	v_fma_f32 v79, -v38, v64, v79
	v_fma_f32 v79, -v39, v65, v79
	v_fma_f32 v79, -v40, v66, v79
	v_fma_f32 v79, -v41, v67, v79
	v_fma_f32 v79, -v84, v68, v79
	v_fma_f32 v79, -v85, v69, v79
	v_fma_f32 v79, -v86, v70, v79
	v_fma_f32 v79, -v87, v71, v79
	v_fma_f32 v79, -v88, v72, v79
	v_fma_f32 v79, -v89, v73, v79
	v_fma_f32 v79, -v90, v74, v79
	v_fma_f32 v79, -v91, v75, v79
	v_fma_f32 v79, -v92, v76, v79
	v_fma_f32 v79, -v93, v77, v79
	v_fma_f32 v79, -v94, v78, v79
	s_waitcnt lgkmcnt(7)
	v_fma_f32 v80, -v2, v45, v80
	ds_read_u16 v22, v63 offset:8976
	ds_read_b32 v23, v62 offset:132
	ds_read_b128 v[6:9], v57 offset:8976
	ds_read_b128 v[14:17], v57 offset:8992
	v_fma_f32 v80, -v3, v46, v80
	s_waitcnt lgkmcnt(3)
	v_lshlrev_b32_e32 v22, 16, v22
	v_fma_f32 v80, -v4, v47, v80
	s_waitcnt lgkmcnt(2)
	v_mul_f32_e32 v81, v23, v22
	v_fma_f32 v80, -v5, v48, v80
	ds_read_b128 v[22:25], v57 offset:9008
	ds_read_b128 v[30:33], v57 offset:9024
	ds_read_b128 v[38:41], v57 offset:9040
	ds_read_b128 v[84:87], v57 offset:9056
	ds_read_b128 v[88:91], v57 offset:9072
	ds_read_b128 v[92:95], v57 offset:9088
	v_fma_f32 v80, -v10, v49, v80
	v_fma_f32 v80, -v11, v50, v80
	v_fma_f32 v80, -v12, v51, v80
	v_fma_f32 v80, -v13, v52, v80
	v_fma_f32 v80, -v18, v53, v80
	v_fma_f32 v80, -v19, v54, v80
	v_fma_f32 v80, -v20, v55, v80
	v_fma_f32 v80, -v21, v56, v80
	v_fma_f32 v80, -v26, v58, v80
	v_fma_f32 v80, -v27, v59, v80
	v_fma_f32 v80, -v28, v60, v80
	v_fma_f32 v80, -v29, v61, v80
	v_fma_f32 v80, -v34, v64, v80
	v_fma_f32 v80, -v35, v65, v80
	v_fma_f32 v80, -v36, v66, v80
	v_fma_f32 v80, -v37, v67, v80
	v_fma_f32 v80, -v106, v68, v80
	v_fma_f32 v80, -v107, v69, v80
	v_fma_f32 v80, -v108, v70, v80
	v_fma_f32 v80, -v109, v71, v80
	v_fma_f32 v80, -v110, v72, v80
	v_fma_f32 v80, -v111, v73, v80
	v_fma_f32 v80, -v112, v74, v80
	v_fma_f32 v80, -v113, v75, v80
	v_fma_f32 v80, -v114, v76, v80
	v_fma_f32 v80, -v115, v77, v80
	v_fma_f32 v80, -v116, v78, v80
	v_fma_f32 v80, -v117, v79, v80
	s_waitcnt lgkmcnt(7)
	v_fma_f32 v81, -v6, v45, v81
	ds_read_u16 v18, v63 offset:9248
	ds_read_b32 v19, v62 offset:136
	ds_read_b128 v[2:5], v57 offset:9104
	ds_read_b128 v[10:13], v57 offset:9248
	v_fma_f32 v81, -v7, v46, v81
	s_waitcnt lgkmcnt(1)
	v_lshlrev_b32_e32 v3, 16, v18
	v_fma_f32 v81, -v8, v47, v81
	v_mul_f32_e32 v82, v19, v3
	v_fma_f32 v81, -v9, v48, v81
	ds_read_b128 v[18:21], v57 offset:9264
	ds_read_b128 v[26:29], v57 offset:9280
	ds_read_b128 v[34:37], v57 offset:9296
	ds_read_b128 v[106:109], v57 offset:9312
	ds_read_b128 v[110:113], v57 offset:9328
	ds_read_b128 v[114:117], v57 offset:9344
	ds_read_b128 v[120:123], v57 offset:9360
	v_fma_f32 v81, -v14, v49, v81
	v_fma_f32 v81, -v15, v50, v81
	v_fma_f32 v81, -v16, v51, v81
	v_fma_f32 v81, -v17, v52, v81
	v_fma_f32 v81, -v22, v53, v81
	v_fma_f32 v81, -v23, v54, v81
	v_fma_f32 v81, -v24, v55, v81
	v_fma_f32 v81, -v25, v56, v81
	v_fma_f32 v81, -v30, v58, v81
	v_fma_f32 v81, -v31, v59, v81
	v_fma_f32 v81, -v32, v60, v81
	v_fma_f32 v81, -v33, v61, v81
	v_fma_f32 v81, -v38, v64, v81
	v_fma_f32 v81, -v39, v65, v81
	v_fma_f32 v81, -v40, v66, v81
	v_fma_f32 v81, -v41, v67, v81
	v_fma_f32 v81, -v84, v68, v81
	v_fma_f32 v81, -v85, v69, v81
	v_fma_f32 v81, -v86, v70, v81
	v_fma_f32 v81, -v87, v71, v81
	v_fma_f32 v81, -v88, v72, v81
	v_fma_f32 v81, -v89, v73, v81
	v_fma_f32 v81, -v90, v74, v81
	v_fma_f32 v81, -v91, v75, v81
	v_fma_f32 v81, -v92, v76, v81
	v_fma_f32 v81, -v93, v77, v81
	v_fma_f32 v81, -v94, v78, v81
	v_fma_f32 v81, -v95, v79, v81
	v_fma_f32 v81, -v2, v80, v81
	s_waitcnt lgkmcnt(7)
	v_fma_f32 v82, -v10, v45, v82
	ds_read_u16 v8, v63 offset:9520
	ds_read_b32 v9, v62 offset:140
	ds_read_b128 v[2:5], v57 offset:9376
	v_fma_f32 v82, -v11, v46, v82
	s_waitcnt lgkmcnt(0)
	ds_read_b128 v[4:7], v57 offset:9520
	v_fma_f32 v82, -v12, v47, v82
	ds_read_b128 v[14:17], v57 offset:9536
	ds_read_b128 v[22:25], v57 offset:9552
	ds_read_b128 v[30:33], v57 offset:9568
	ds_read_b128 v[38:41], v57 offset:9584
	ds_read_b128 v[86:89], v57 offset:9600
	ds_read_b128 v[90:93], v57 offset:9616
	ds_read_b128 v[94:97], v57 offset:9632
	v_fma_f32 v82, -v13, v48, v82
	v_lshlrev_b32_e32 v8, 16, v8
	v_fma_f32 v82, -v18, v49, v82
	v_mul_f32_e32 v83, v9, v8
	v_fma_f32 v82, -v19, v50, v82
	v_fma_f32 v82, -v20, v51, v82
	v_fma_f32 v82, -v21, v52, v82
	v_fma_f32 v82, -v26, v53, v82
	v_fma_f32 v82, -v27, v54, v82
	v_fma_f32 v82, -v28, v55, v82
	v_fma_f32 v82, -v29, v56, v82
	v_fma_f32 v82, -v34, v58, v82
	v_fma_f32 v82, -v35, v59, v82
	v_fma_f32 v82, -v36, v60, v82
	v_fma_f32 v82, -v37, v61, v82
	v_fma_f32 v82, -v106, v64, v82
	v_fma_f32 v82, -v107, v65, v82
	v_fma_f32 v82, -v108, v66, v82
	v_fma_f32 v82, -v109, v67, v82
	v_fma_f32 v82, -v110, v68, v82
	v_fma_f32 v82, -v111, v69, v82
	v_fma_f32 v82, -v112, v70, v82
	v_fma_f32 v82, -v113, v71, v82
	v_fma_f32 v82, -v114, v72, v82
	v_fma_f32 v82, -v115, v73, v82
	v_fma_f32 v82, -v116, v74, v82
	v_fma_f32 v82, -v117, v75, v82
	v_fma_f32 v82, -v120, v76, v82
	v_fma_f32 v82, -v121, v77, v82
	v_fma_f32 v82, -v122, v78, v82
	v_fma_f32 v82, -v123, v79, v82
	v_fma_f32 v82, -v2, v80, v82
	v_fma_f32 v82, -v3, v81, v82
	s_waitcnt lgkmcnt(7)
	v_fma_f32 v83, -v4, v45, v83
	ds_read_u16 v2, v63 offset:9792
	ds_read_b32 v3, v62 offset:144
	ds_read_b128 v[8:11], v57 offset:9648
	ds_read_b128 v[18:21], v57 offset:9792
	v_fma_f32 v83, -v5, v46, v83
	ds_read_b128 v[26:29], v57 offset:9808
	ds_read_b128 v[34:37], v57 offset:9824
	ds_read_b128 v[106:109], v57 offset:9840
	ds_read_b128 v[110:113], v57 offset:9856
	ds_read_b128 v[114:117], v57 offset:9872
	ds_read_b128 v[120:123], v57 offset:9888
	ds_read_b128 v[124:127], v57 offset:9904
	v_fma_f32 v83, -v6, v47, v83
	s_waitcnt lgkmcnt(10)
	v_lshlrev_b32_e32 v2, 16, v2
	v_fma_f32 v83, -v7, v48, v83
	s_waitcnt lgkmcnt(9)
	v_mul_f32_e32 v84, v3, v2
	v_fma_f32 v83, -v14, v49, v83
	v_fma_f32 v83, -v15, v50, v83
	v_fma_f32 v83, -v16, v51, v83
	v_fma_f32 v83, -v17, v52, v83
	v_fma_f32 v83, -v22, v53, v83
	v_fma_f32 v83, -v23, v54, v83
	v_fma_f32 v83, -v24, v55, v83
	v_fma_f32 v83, -v25, v56, v83
	v_fma_f32 v83, -v30, v58, v83
	v_fma_f32 v83, -v31, v59, v83
	v_fma_f32 v83, -v32, v60, v83
	v_fma_f32 v83, -v33, v61, v83
	v_fma_f32 v83, -v38, v64, v83
	v_fma_f32 v83, -v39, v65, v83
	v_fma_f32 v83, -v40, v66, v83
	v_fma_f32 v83, -v41, v67, v83
	v_fma_f32 v83, -v86, v68, v83
	v_fma_f32 v83, -v87, v69, v83
	v_fma_f32 v83, -v88, v70, v83
	v_fma_f32 v83, -v89, v71, v83
	v_fma_f32 v83, -v90, v72, v83
	v_fma_f32 v83, -v91, v73, v83
	v_fma_f32 v83, -v92, v74, v83
	v_fma_f32 v83, -v93, v75, v83
	v_fma_f32 v83, -v94, v76, v83
	v_fma_f32 v83, -v95, v77, v83
	v_fma_f32 v83, -v96, v78, v83
	v_fma_f32 v83, -v97, v79, v83
	s_waitcnt lgkmcnt(8)
	v_fma_f32 v83, -v8, v80, v83
	v_fma_f32 v83, -v9, v81, v83
	v_fma_f32 v83, -v10, v82, v83
	s_waitcnt lgkmcnt(7)
	v_fma_f32 v84, -v18, v45, v84
	ds_read_u16 v10, v63 offset:10064
	ds_read_b32 v11, v62 offset:148
	ds_read_b128 v[2:5], v57 offset:9920
	ds_read_b128 v[6:9], v57 offset:10064
	v_fma_f32 v84, -v19, v46, v84
	s_waitcnt lgkmcnt(3)
	v_lshlrev_b32_e32 v10, 16, v10
	v_fma_f32 v84, -v20, v47, v84
	s_waitcnt lgkmcnt(2)
	v_mul_f32_e32 v85, v11, v10
	v_fma_f32 v84, -v21, v48, v84
	ds_read_b128 v[10:13], v57 offset:10080
	ds_read_b128 v[14:17], v57 offset:10096
	ds_read_b128 v[22:25], v57 offset:10112
	ds_read_b128 v[30:33], v57 offset:10128
	ds_read_b128 v[38:41], v57 offset:10144
	ds_read_b128 v[88:91], v57 offset:10160
	ds_read_b128 v[92:95], v57 offset:10176
	v_fma_f32 v84, -v26, v49, v84
	v_fma_f32 v84, -v27, v50, v84
	v_fma_f32 v84, -v28, v51, v84
	v_fma_f32 v84, -v29, v52, v84
	v_fma_f32 v84, -v34, v53, v84
	v_fma_f32 v84, -v35, v54, v84
	v_fma_f32 v84, -v36, v55, v84
	v_fma_f32 v84, -v37, v56, v84
	v_fma_f32 v84, -v106, v58, v84
	v_fma_f32 v84, -v107, v59, v84
	v_fma_f32 v84, -v108, v60, v84
	v_fma_f32 v84, -v109, v61, v84
	v_fma_f32 v84, -v110, v64, v84
	v_fma_f32 v84, -v111, v65, v84
	v_fma_f32 v84, -v112, v66, v84
	v_fma_f32 v84, -v113, v67, v84
	v_fma_f32 v84, -v114, v68, v84
	v_fma_f32 v84, -v115, v69, v84
	v_fma_f32 v84, -v116, v70, v84
	v_fma_f32 v84, -v117, v71, v84
	v_fma_f32 v84, -v120, v72, v84
	v_fma_f32 v84, -v121, v73, v84
	v_fma_f32 v84, -v122, v74, v84
	v_fma_f32 v84, -v123, v75, v84
	v_fma_f32 v84, -v124, v76, v84
	v_fma_f32 v84, -v125, v77, v84
	v_fma_f32 v84, -v126, v78, v84
	v_fma_f32 v84, -v127, v79, v84
	s_waitcnt lgkmcnt(8)
	v_fma_f32 v84, -v2, v80, v84
	v_fma_f32 v84, -v3, v81, v84
	v_fma_f32 v84, -v4, v82, v84
	v_fma_f32 v84, -v5, v83, v84
	s_waitcnt lgkmcnt(7)
	v_fma_f32 v85, -v6, v45, v85
	ds_read_u16 v26, v63 offset:10336
	ds_read_b32 v27, v62 offset:152
	ds_read_b128 v[2:5], v57 offset:10192
	ds_read_b128 v[18:21], v57 offset:10208
	v_fma_f32 v85, -v7, v46, v85
	s_waitcnt lgkmcnt(0)
	v_lshlrev_b32_e32 v19, 16, v26
	v_fma_f32 v85, -v8, v47, v85
	v_mul_f32_e32 v86, v27, v19
	v_fma_f32 v85, -v9, v48, v85
	ds_read_b128 v[26:29], v57 offset:10336
	ds_read_b128 v[34:37], v57 offset:10352
	ds_read_b128 v[106:109], v57 offset:10368
	ds_read_b128 v[110:113], v57 offset:10384
	ds_read_b128 v[114:117], v57 offset:10400
	ds_read_b128 v[120:123], v57 offset:10416
	ds_read_b128 v[124:127], v57 offset:10432
	ds_read_b128 v[128:131], v57 offset:10448
	v_fma_f32 v85, -v10, v49, v85
	v_fma_f32 v85, -v11, v50, v85
	v_fma_f32 v85, -v12, v51, v85
	v_fma_f32 v85, -v13, v52, v85
	v_fma_f32 v85, -v14, v53, v85
	v_fma_f32 v85, -v15, v54, v85
	v_fma_f32 v85, -v16, v55, v85
	v_fma_f32 v85, -v17, v56, v85
	v_fma_f32 v85, -v22, v58, v85
	v_fma_f32 v85, -v23, v59, v85
	v_fma_f32 v85, -v24, v60, v85
	v_fma_f32 v85, -v25, v61, v85
	v_fma_f32 v85, -v30, v64, v85
	v_fma_f32 v85, -v31, v65, v85
	v_fma_f32 v85, -v32, v66, v85
	v_fma_f32 v85, -v33, v67, v85
	v_fma_f32 v85, -v38, v68, v85
	v_fma_f32 v85, -v39, v69, v85
	v_fma_f32 v85, -v40, v70, v85
	v_fma_f32 v85, -v41, v71, v85
	v_fma_f32 v85, -v88, v72, v85
	v_fma_f32 v85, -v89, v73, v85
	v_fma_f32 v85, -v90, v74, v85
	v_fma_f32 v85, -v91, v75, v85
	v_fma_f32 v85, -v92, v76, v85
	v_fma_f32 v85, -v93, v77, v85
	v_fma_f32 v85, -v94, v78, v85
	v_fma_f32 v85, -v95, v79, v85
	v_fma_f32 v85, -v2, v80, v85
	v_fma_f32 v85, -v3, v81, v85
	v_fma_f32 v85, -v4, v82, v85
	v_fma_f32 v85, -v5, v83, v85
	v_fma_f32 v85, -v18, v84, v85
	s_waitcnt lgkmcnt(7)
	v_fma_f32 v86, -v26, v45, v86
	ds_read_u16 v10, v63 offset:10608
	ds_read_b32 v11, v62 offset:156
	ds_read_b128 v[2:5], v57 offset:10464
	ds_read_b128 v[6:9], v57 offset:10480
	v_fma_f32 v86, -v27, v46, v86
	s_waitcnt lgkmcnt(0)
	v_lshlrev_b32_e32 v8, 16, v10
	v_fma_f32 v86, -v28, v47, v86
	v_mul_f32_e32 v87, v11, v8
	v_fma_f32 v86, -v29, v48, v86
	ds_read_b128 v[8:11], v57 offset:10608
	ds_read_b128 v[12:15], v57 offset:10624
	ds_read_b128 v[16:19], v57 offset:10640
	ds_read_b128 v[20:23], v57 offset:10656
	ds_read_b128 v[30:33], v57 offset:10672
	ds_read_b128 v[38:41], v57 offset:10688
	ds_read_b128 v[90:93], v57 offset:10704
	ds_read_b128 v[94:97], v57 offset:10720
	v_fma_f32 v86, -v34, v49, v86
	v_fma_f32 v86, -v35, v50, v86
	v_fma_f32 v86, -v36, v51, v86
	v_fma_f32 v86, -v37, v52, v86
	v_fma_f32 v86, -v106, v53, v86
	v_fma_f32 v86, -v107, v54, v86
	v_fma_f32 v86, -v108, v55, v86
	v_fma_f32 v86, -v109, v56, v86
	v_fma_f32 v86, -v110, v58, v86
	v_fma_f32 v86, -v111, v59, v86
	v_fma_f32 v86, -v112, v60, v86
	v_fma_f32 v86, -v113, v61, v86
	v_fma_f32 v86, -v114, v64, v86
	v_fma_f32 v86, -v115, v65, v86
	v_fma_f32 v86, -v116, v66, v86
	v_fma_f32 v86, -v117, v67, v86
	v_fma_f32 v86, -v120, v68, v86
	v_fma_f32 v86, -v121, v69, v86
	v_fma_f32 v86, -v122, v70, v86
	v_fma_f32 v86, -v123, v71, v86
	v_fma_f32 v86, -v124, v72, v86
	v_fma_f32 v86, -v125, v73, v86
	v_fma_f32 v86, -v126, v74, v86
	v_fma_f32 v86, -v127, v75, v86
	v_fma_f32 v86, -v128, v76, v86
	v_fma_f32 v86, -v129, v77, v86
	v_fma_f32 v86, -v130, v78, v86
	v_fma_f32 v86, -v131, v79, v86
	v_fma_f32 v86, -v2, v80, v86
	v_fma_f32 v86, -v3, v81, v86
	v_fma_f32 v86, -v4, v82, v86
	v_fma_f32 v86, -v5, v83, v86
	v_fma_f32 v86, -v6, v84, v86
	v_fma_f32 v86, -v7, v85, v86
	s_waitcnt lgkmcnt(7)
	v_fma_f32 v87, -v8, v45, v87
	ds_read_u16 v6, v63 offset:10880
	ds_read_b32 v7, v62 offset:160
	ds_read_b128 v[2:5], v57 offset:10736
	ds_read_b128 v[24:27], v57 offset:10752
	v_fma_f32 v87, -v9, v46, v87
	ds_read_b128 v[34:37], v57 offset:10880
	ds_read_b128 v[106:109], v57 offset:10896
	ds_read_b128 v[110:113], v57 offset:10912
	ds_read_b128 v[114:117], v57 offset:10928
	ds_read_b128 v[120:123], v57 offset:10944
	ds_read_b128 v[124:127], v57 offset:10960
	ds_read_b128 v[128:131], v57 offset:10976
	ds_read_b128 v[132:135], v57 offset:10992
	v_fma_f32 v87, -v10, v47, v87
	s_waitcnt lgkmcnt(11)
	v_lshlrev_b32_e32 v6, 16, v6
	v_fma_f32 v87, -v11, v48, v87
	s_waitcnt lgkmcnt(10)
	v_mul_f32_e32 v88, v7, v6
	v_fma_f32 v87, -v12, v49, v87
	v_fma_f32 v87, -v13, v50, v87
	v_fma_f32 v87, -v14, v51, v87
	v_fma_f32 v87, -v15, v52, v87
	v_fma_f32 v87, -v16, v53, v87
	v_fma_f32 v87, -v17, v54, v87
	v_fma_f32 v87, -v18, v55, v87
	v_fma_f32 v87, -v19, v56, v87
	v_fma_f32 v87, -v20, v58, v87
	v_fma_f32 v87, -v21, v59, v87
	v_fma_f32 v87, -v22, v60, v87
	v_fma_f32 v87, -v23, v61, v87
	v_fma_f32 v87, -v30, v64, v87
	v_fma_f32 v87, -v31, v65, v87
	v_fma_f32 v87, -v32, v66, v87
	v_fma_f32 v87, -v33, v67, v87
	v_fma_f32 v87, -v38, v68, v87
	v_fma_f32 v87, -v39, v69, v87
	v_fma_f32 v87, -v40, v70, v87
	v_fma_f32 v87, -v41, v71, v87
	v_fma_f32 v87, -v90, v72, v87
	v_fma_f32 v87, -v91, v73, v87
	v_fma_f32 v87, -v92, v74, v87
	v_fma_f32 v87, -v93, v75, v87
	v_fma_f32 v87, -v94, v76, v87
	v_fma_f32 v87, -v95, v77, v87
	v_fma_f32 v87, -v96, v78, v87
	v_fma_f32 v87, -v97, v79, v87
	s_waitcnt lgkmcnt(9)
	v_fma_f32 v87, -v2, v80, v87
	v_fma_f32 v87, -v3, v81, v87
	v_fma_f32 v87, -v4, v82, v87
	v_fma_f32 v87, -v5, v83, v87
	s_waitcnt lgkmcnt(8)
	v_fma_f32 v87, -v24, v84, v87
	v_fma_f32 v87, -v25, v85, v87
	v_fma_f32 v87, -v26, v86, v87
	s_waitcnt lgkmcnt(7)
	v_fma_f32 v88, -v34, v45, v88
	ds_read_u16 v10, v63 offset:11152
	ds_read_b32 v11, v62 offset:164
	ds_read_b128 v[2:5], v57 offset:11008
	ds_read_b128 v[6:9], v57 offset:11024
	v_fma_f32 v88, -v35, v46, v88
	s_waitcnt lgkmcnt(3)
	v_lshlrev_b32_e32 v10, 16, v10
	v_fma_f32 v88, -v36, v47, v88
	s_waitcnt lgkmcnt(2)
	v_mul_f32_e32 v89, v11, v10
	v_fma_f32 v88, -v37, v48, v88
	ds_read_b128 v[10:13], v57 offset:11152
	ds_read_b128 v[14:17], v57 offset:11168
	ds_read_b128 v[18:21], v57 offset:11184
	ds_read_b128 v[22:25], v57 offset:11200
	ds_read_b128 v[26:29], v57 offset:11216
	ds_read_b128 v[30:33], v57 offset:11232
	ds_read_b128 v[38:41], v57 offset:11248
	ds_read_b128 v[92:95], v57 offset:11264
	v_fma_f32 v88, -v106, v49, v88
	v_fma_f32 v88, -v107, v50, v88
	v_fma_f32 v88, -v108, v51, v88
	v_fma_f32 v88, -v109, v52, v88
	v_fma_f32 v88, -v110, v53, v88
	v_fma_f32 v88, -v111, v54, v88
	v_fma_f32 v88, -v112, v55, v88
	v_fma_f32 v88, -v113, v56, v88
	v_fma_f32 v88, -v114, v58, v88
	v_fma_f32 v88, -v115, v59, v88
	v_fma_f32 v88, -v116, v60, v88
	v_fma_f32 v88, -v117, v61, v88
	v_fma_f32 v88, -v120, v64, v88
	v_fma_f32 v88, -v121, v65, v88
	v_fma_f32 v88, -v122, v66, v88
	v_fma_f32 v88, -v123, v67, v88
	v_fma_f32 v88, -v124, v68, v88
	v_fma_f32 v88, -v125, v69, v88
	v_fma_f32 v88, -v126, v70, v88
	v_fma_f32 v88, -v127, v71, v88
	v_fma_f32 v88, -v128, v72, v88
	v_fma_f32 v88, -v129, v73, v88
	v_fma_f32 v88, -v130, v74, v88
	v_fma_f32 v88, -v131, v75, v88
	v_fma_f32 v88, -v132, v76, v88
	v_fma_f32 v88, -v133, v77, v88
	v_fma_f32 v88, -v134, v78, v88
	v_fma_f32 v88, -v135, v79, v88
	s_waitcnt lgkmcnt(9)
	v_fma_f32 v88, -v2, v80, v88
	v_fma_f32 v88, -v3, v81, v88
	v_fma_f32 v88, -v4, v82, v88
	v_fma_f32 v88, -v5, v83, v88
	s_waitcnt lgkmcnt(8)
	v_fma_f32 v88, -v6, v84, v88
	v_fma_f32 v88, -v7, v85, v88
	v_fma_f32 v88, -v8, v86, v88
	v_fma_f32 v88, -v9, v87, v88
	s_waitcnt lgkmcnt(7)
	v_fma_f32 v89, -v10, v45, v89
	ds_read_u16 v34, v63 offset:11424
	ds_read_b32 v35, v62 offset:168
	ds_read_b128 v[2:5], v57 offset:11280
	ds_read_b128 v[6:9], v57 offset:11296
	v_fma_f32 v89, -v11, v46, v89
	s_waitcnt lgkmcnt(3)
	v_lshlrev_b32_e32 v34, 16, v34
	v_fma_f32 v89, -v12, v47, v89
	s_waitcnt lgkmcnt(2)
	v_mul_f32_e32 v90, v35, v34
	v_fma_f32 v89, -v13, v48, v89
	ds_read_b128 v[34:37], v57 offset:11312
	ds_read_b128 v[106:109], v57 offset:11424
	ds_read_b128 v[110:113], v57 offset:11440
	ds_read_b128 v[114:117], v57 offset:11456
	ds_read_b128 v[120:123], v57 offset:11472
	ds_read_b128 v[124:127], v57 offset:11488
	ds_read_b128 v[128:131], v57 offset:11504
	ds_read_b128 v[132:135], v57 offset:11520
	ds_read_b128 v[144:147], v57 offset:11536
	v_fma_f32 v89, -v14, v49, v89
	v_fma_f32 v89, -v15, v50, v89
	v_fma_f32 v89, -v16, v51, v89
	v_fma_f32 v89, -v17, v52, v89
	v_fma_f32 v89, -v18, v53, v89
	v_fma_f32 v89, -v19, v54, v89
	v_fma_f32 v89, -v20, v55, v89
	v_fma_f32 v89, -v21, v56, v89
	v_fma_f32 v89, -v22, v58, v89
	v_fma_f32 v89, -v23, v59, v89
	v_fma_f32 v89, -v24, v60, v89
	v_fma_f32 v89, -v25, v61, v89
	v_fma_f32 v89, -v26, v64, v89
	v_fma_f32 v89, -v27, v65, v89
	v_fma_f32 v89, -v28, v66, v89
	v_fma_f32 v89, -v29, v67, v89
	v_fma_f32 v89, -v30, v68, v89
	v_fma_f32 v89, -v31, v69, v89
	v_fma_f32 v89, -v32, v70, v89
	v_fma_f32 v89, -v33, v71, v89
	v_fma_f32 v89, -v38, v72, v89
	v_fma_f32 v89, -v39, v73, v89
	v_fma_f32 v89, -v40, v74, v89
	v_fma_f32 v89, -v41, v75, v89
	v_fma_f32 v89, -v92, v76, v89
	v_fma_f32 v89, -v93, v77, v89
	v_fma_f32 v89, -v94, v78, v89
	v_fma_f32 v89, -v95, v79, v89
	s_waitcnt lgkmcnt(10)
	v_fma_f32 v89, -v2, v80, v89
	v_fma_f32 v89, -v3, v81, v89
	v_fma_f32 v89, -v4, v82, v89
	v_fma_f32 v89, -v5, v83, v89
	s_waitcnt lgkmcnt(9)
	v_fma_f32 v89, -v6, v84, v89
	v_fma_f32 v89, -v7, v85, v89
	v_fma_f32 v89, -v8, v86, v89
	v_fma_f32 v89, -v9, v87, v89
	s_waitcnt lgkmcnt(8)
	v_fma_f32 v89, -v34, v88, v89
	s_waitcnt lgkmcnt(7)
	v_fma_f32 v90, -v106, v45, v90
	ds_read_u16 v10, v63 offset:11696
	ds_read_b32 v11, v62 offset:172
	ds_read_b128 v[2:5], v57 offset:11552
	ds_read_b128 v[6:9], v57 offset:11568
	v_fma_f32 v90, -v107, v46, v90
	s_waitcnt lgkmcnt(3)
	v_lshlrev_b32_e32 v10, 16, v10
	v_fma_f32 v90, -v108, v47, v90
	s_waitcnt lgkmcnt(2)
	v_mul_f32_e32 v91, v11, v10
	v_fma_f32 v90, -v109, v48, v90
	ds_read_b128 v[10:13], v57 offset:11584
	v_fma_f32 v90, -v110, v49, v90
	s_waitcnt lgkmcnt(0)
	ds_read_b128 v[12:15], v57 offset:11696
	ds_read_b128 v[16:19], v57 offset:11712
	ds_read_b128 v[20:23], v57 offset:11728
	ds_read_b128 v[24:27], v57 offset:11744
	ds_read_b128 v[28:31], v57 offset:11760
	ds_read_b128 v[32:35], v57 offset:11776
	ds_read_b128 v[36:39], v57 offset:11792
	ds_read_b128 v[94:97], v57 offset:11808
	v_fma_f32 v90, -v111, v50, v90
	v_fma_f32 v90, -v112, v51, v90
	v_fma_f32 v90, -v113, v52, v90
	v_fma_f32 v90, -v114, v53, v90
	v_fma_f32 v90, -v115, v54, v90
	v_fma_f32 v90, -v116, v55, v90
	v_fma_f32 v90, -v117, v56, v90
	v_fma_f32 v90, -v120, v58, v90
	v_fma_f32 v90, -v121, v59, v90
	v_fma_f32 v90, -v122, v60, v90
	v_fma_f32 v90, -v123, v61, v90
	v_fma_f32 v90, -v124, v64, v90
	v_fma_f32 v90, -v125, v65, v90
	v_fma_f32 v90, -v126, v66, v90
	v_fma_f32 v90, -v127, v67, v90
	v_fma_f32 v90, -v128, v68, v90
	v_fma_f32 v90, -v129, v69, v90
	v_fma_f32 v90, -v130, v70, v90
	v_fma_f32 v90, -v131, v71, v90
	v_fma_f32 v90, -v132, v72, v90
	v_fma_f32 v90, -v133, v73, v90
	v_fma_f32 v90, -v134, v74, v90
	v_fma_f32 v90, -v135, v75, v90
	v_fma_f32 v90, -v144, v76, v90
	v_fma_f32 v90, -v145, v77, v90
	v_fma_f32 v90, -v146, v78, v90
	v_fma_f32 v90, -v147, v79, v90
	v_fma_f32 v90, -v2, v80, v90
	v_fma_f32 v90, -v3, v81, v90
	v_fma_f32 v90, -v4, v82, v90
	v_fma_f32 v90, -v5, v83, v90
	v_fma_f32 v90, -v6, v84, v90
	v_fma_f32 v90, -v7, v85, v90
	v_fma_f32 v90, -v8, v86, v90
	v_fma_f32 v90, -v9, v87, v90
	v_fma_f32 v90, -v10, v88, v90
	v_fma_f32 v90, -v11, v89, v90
	s_waitcnt lgkmcnt(7)
	v_fma_f32 v91, -v12, v45, v91
	ds_read_u16 v10, v63 offset:11968
	ds_read_b32 v11, v62 offset:176
	ds_read_b128 v[2:5], v57 offset:11824
	ds_read_b128 v[6:9], v57 offset:11840
	v_fma_f32 v91, -v13, v46, v91
	s_waitcnt lgkmcnt(3)
	v_lshlrev_b32_e32 v10, 16, v10
	v_fma_f32 v91, -v14, v47, v91
	ds_read_b128 v[106:109], v57 offset:11856
	ds_read_b128 v[110:113], v57 offset:11968
	ds_read_b128 v[114:117], v57 offset:11984
	ds_read_b128 v[120:123], v57 offset:12000
	ds_read_b128 v[124:127], v57 offset:12016
	ds_read_b128 v[128:131], v57 offset:12032
	ds_read_b128 v[132:135], v57 offset:12048
	ds_read_b128 v[144:147], v57 offset:12064
	ds_read_b128 v[148:151], v57 offset:12080
	v_fma_f32 v91, -v15, v48, v91
	s_waitcnt lgkmcnt(11)
	v_mul_f32_e32 v92, v11, v10
	v_fma_f32 v91, -v16, v49, v91
	v_fma_f32 v91, -v17, v50, v91
	v_fma_f32 v91, -v18, v51, v91
	v_fma_f32 v91, -v19, v52, v91
	v_fma_f32 v91, -v20, v53, v91
	v_fma_f32 v91, -v21, v54, v91
	v_fma_f32 v91, -v22, v55, v91
	v_fma_f32 v91, -v23, v56, v91
	v_fma_f32 v91, -v24, v58, v91
	v_fma_f32 v91, -v25, v59, v91
	v_fma_f32 v91, -v26, v60, v91
	v_fma_f32 v91, -v27, v61, v91
	v_fma_f32 v91, -v28, v64, v91
	v_fma_f32 v91, -v29, v65, v91
	v_fma_f32 v91, -v30, v66, v91
	v_fma_f32 v91, -v31, v67, v91
	v_fma_f32 v91, -v32, v68, v91
	v_fma_f32 v91, -v33, v69, v91
	v_fma_f32 v91, -v34, v70, v91
	v_fma_f32 v91, -v35, v71, v91
	v_fma_f32 v91, -v36, v72, v91
	v_fma_f32 v91, -v37, v73, v91
	v_fma_f32 v91, -v38, v74, v91
	v_fma_f32 v91, -v39, v75, v91
	v_fma_f32 v91, -v94, v76, v91
	v_fma_f32 v91, -v95, v77, v91
	v_fma_f32 v91, -v96, v78, v91
	v_fma_f32 v91, -v97, v79, v91
	s_waitcnt lgkmcnt(10)
	v_fma_f32 v91, -v2, v80, v91
	v_fma_f32 v91, -v3, v81, v91
	v_fma_f32 v91, -v4, v82, v91
	v_fma_f32 v91, -v5, v83, v91
	s_waitcnt lgkmcnt(9)
	v_fma_f32 v91, -v6, v84, v91
	v_fma_f32 v91, -v7, v85, v91
	v_fma_f32 v91, -v8, v86, v91
	v_fma_f32 v91, -v9, v87, v91
	s_waitcnt lgkmcnt(8)
	v_fma_f32 v91, -v106, v88, v91
	v_fma_f32 v91, -v107, v89, v91
	v_fma_f32 v91, -v108, v90, v91
	s_waitcnt lgkmcnt(7)
	v_fma_f32 v92, -v110, v45, v92
	ds_read_u16 v10, v63 offset:12240
	ds_read_b32 v11, v62 offset:180
	ds_read_b128 v[2:5], v57 offset:12096
	ds_read_b128 v[6:9], v57 offset:12112
	v_fma_f32 v92, -v111, v46, v92
	s_waitcnt lgkmcnt(3)
	v_lshlrev_b32_e32 v10, 16, v10
	v_fma_f32 v92, -v112, v47, v92
	s_waitcnt lgkmcnt(2)
	v_mul_f32_e32 v93, v11, v10
	v_fma_f32 v92, -v113, v48, v92
	ds_read_b128 v[10:13], v57 offset:12128
	ds_read_b128 v[14:17], v57 offset:12240
	ds_read_b128 v[18:21], v57 offset:12256
	ds_read_b128 v[22:25], v57 offset:12272
	ds_read_b128 v[26:29], v57 offset:12288
	ds_read_b128 v[30:33], v57 offset:12304
	ds_read_b128 v[34:37], v57 offset:12320
	ds_read_b128 v[38:41], v57 offset:12336
	ds_read_b128 v[106:109], v57 offset:12352
	v_fma_f32 v92, -v114, v49, v92
	v_fma_f32 v92, -v115, v50, v92
	v_fma_f32 v92, -v116, v51, v92
	v_fma_f32 v92, -v117, v52, v92
	v_fma_f32 v92, -v120, v53, v92
	v_fma_f32 v92, -v121, v54, v92
	v_fma_f32 v92, -v122, v55, v92
	v_fma_f32 v92, -v123, v56, v92
	v_fma_f32 v92, -v124, v58, v92
	v_fma_f32 v92, -v125, v59, v92
	v_fma_f32 v92, -v126, v60, v92
	v_fma_f32 v92, -v127, v61, v92
	v_fma_f32 v92, -v128, v64, v92
	v_fma_f32 v92, -v129, v65, v92
	v_fma_f32 v92, -v130, v66, v92
	v_fma_f32 v92, -v131, v67, v92
	v_fma_f32 v92, -v132, v68, v92
	v_fma_f32 v92, -v133, v69, v92
	v_fma_f32 v92, -v134, v70, v92
	v_fma_f32 v92, -v135, v71, v92
	v_fma_f32 v92, -v144, v72, v92
	v_fma_f32 v92, -v145, v73, v92
	v_fma_f32 v92, -v146, v74, v92
	v_fma_f32 v92, -v147, v75, v92
	v_fma_f32 v92, -v148, v76, v92
	v_fma_f32 v92, -v149, v77, v92
	v_fma_f32 v92, -v150, v78, v92
	v_fma_f32 v92, -v151, v79, v92
	s_waitcnt lgkmcnt(10)
	v_fma_f32 v92, -v2, v80, v92
	v_fma_f32 v92, -v3, v81, v92
	v_fma_f32 v92, -v4, v82, v92
	v_fma_f32 v92, -v5, v83, v92
	s_waitcnt lgkmcnt(9)
	v_fma_f32 v92, -v6, v84, v92
	v_fma_f32 v92, -v7, v85, v92
	v_fma_f32 v92, -v8, v86, v92
	v_fma_f32 v92, -v9, v87, v92
	s_waitcnt lgkmcnt(8)
	v_fma_f32 v92, -v10, v88, v92
	v_fma_f32 v92, -v11, v89, v92
	v_fma_f32 v92, -v12, v90, v92
	v_fma_f32 v92, -v13, v91, v92
	s_waitcnt lgkmcnt(7)
	v_fma_f32 v93, -v14, v45, v93
	ds_read_u16 v2, v63 offset:12512
	ds_read_b32 v3, v62 offset:184
	ds_read_b128 v[6:9], v57 offset:12368
	ds_read_b128 v[10:13], v57 offset:12384
	ds_read_b128 v[110:113], v57 offset:12400
	ds_read_b128 v[114:117], v57 offset:12416
	v_fma_f32 v93, -v15, v46, v93
	s_waitcnt lgkmcnt(5)
	v_lshlrev_b32_e32 v2, 16, v2
	v_fma_f32 v93, -v16, v47, v93
	s_waitcnt lgkmcnt(4)
	v_mul_f32_e32 v94, v3, v2
	v_fma_f32 v93, -v17, v48, v93
	ds_read_b128 v[120:123], v57 offset:12512
	ds_read_b128 v[124:127], v57 offset:12528
	ds_read_b128 v[128:131], v57 offset:12544
	ds_read_b128 v[132:135], v57 offset:12560
	ds_read_b128 v[144:147], v57 offset:12576
	ds_read_b128 v[148:151], v57 offset:12592
	ds_read_b128 v[152:155], v57 offset:12608
	ds_read_b128 v[2:5], v57 offset:12624
	v_fma_f32 v93, -v18, v49, v93
	v_fma_f32 v93, -v19, v50, v93
	v_fma_f32 v93, -v20, v51, v93
	v_fma_f32 v93, -v21, v52, v93
	v_fma_f32 v93, -v22, v53, v93
	v_fma_f32 v93, -v23, v54, v93
	v_fma_f32 v93, -v24, v55, v93
	v_fma_f32 v93, -v25, v56, v93
	v_fma_f32 v93, -v26, v58, v93
	v_fma_f32 v93, -v27, v59, v93
	v_fma_f32 v93, -v28, v60, v93
	v_fma_f32 v93, -v29, v61, v93
	v_fma_f32 v93, -v30, v64, v93
	v_fma_f32 v93, -v31, v65, v93
	v_fma_f32 v93, -v32, v66, v93
	v_fma_f32 v93, -v33, v67, v93
	v_fma_f32 v93, -v34, v68, v93
	v_fma_f32 v93, -v35, v69, v93
	v_fma_f32 v93, -v36, v70, v93
	v_fma_f32 v93, -v37, v71, v93
	v_fma_f32 v93, -v38, v72, v93
	v_fma_f32 v93, -v39, v73, v93
	v_fma_f32 v93, -v40, v74, v93
	v_fma_f32 v93, -v41, v75, v93
	v_fma_f32 v93, -v106, v76, v93
	v_fma_f32 v93, -v107, v77, v93
	v_fma_f32 v93, -v108, v78, v93
	v_fma_f32 v93, -v109, v79, v93
	s_waitcnt lgkmcnt(11)
	v_fma_f32 v93, -v6, v80, v93
	v_fma_f32 v93, -v7, v81, v93
	v_fma_f32 v93, -v8, v82, v93
	v_fma_f32 v93, -v9, v83, v93
	s_waitcnt lgkmcnt(10)
	v_fma_f32 v93, -v10, v84, v93
	v_fma_f32 v93, -v11, v85, v93
	v_fma_f32 v93, -v12, v86, v93
	v_fma_f32 v93, -v13, v87, v93
	s_waitcnt lgkmcnt(9)
	v_fma_f32 v93, -v110, v88, v93
	v_fma_f32 v93, -v111, v89, v93
	v_fma_f32 v93, -v112, v90, v93
	v_fma_f32 v93, -v113, v91, v93
	s_waitcnt lgkmcnt(8)
	v_fma_f32 v93, -v114, v92, v93
	s_waitcnt lgkmcnt(7)
	v_fma_f32 v94, -v120, v45, v94
	ds_read_u16 v6, v63 offset:12784
	ds_read_b32 v7, v62 offset:188
	ds_read_b128 v[10:13], v57 offset:12640
	ds_read_b128 v[14:17], v57 offset:12656
	ds_read_b128 v[18:21], v57 offset:12672
	ds_read_b128 v[22:25], v57 offset:12688
	v_fma_f32 v94, -v121, v46, v94
	s_waitcnt lgkmcnt(5)
	v_lshlrev_b32_e32 v6, 16, v6
	v_fma_f32 v94, -v122, v47, v94
	s_waitcnt lgkmcnt(4)
	v_mul_f32_e32 v95, v7, v6
	v_fma_f32 v94, -v123, v48, v94
	s_waitcnt lgkmcnt(0)
	ds_read_b128 v[24:27], v57 offset:12784
	ds_read_b128 v[28:31], v57 offset:12800
	ds_read_b128 v[32:35], v57 offset:12816
	ds_read_b128 v[36:39], v57 offset:12832
	ds_read_b128 v[106:109], v57 offset:12848
	ds_read_b128 v[110:113], v57 offset:12864
	ds_read_b128 v[114:117], v57 offset:12880
	ds_read_b128 v[6:9], v57 offset:12896
	v_fma_f32 v94, -v124, v49, v94
	v_fma_f32 v94, -v125, v50, v94
	v_fma_f32 v94, -v126, v51, v94
	v_fma_f32 v94, -v127, v52, v94
	v_fma_f32 v94, -v128, v53, v94
	v_fma_f32 v94, -v129, v54, v94
	v_fma_f32 v94, -v130, v55, v94
	v_fma_f32 v94, -v131, v56, v94
	v_fma_f32 v94, -v132, v58, v94
	v_fma_f32 v94, -v133, v59, v94
	v_fma_f32 v94, -v134, v60, v94
	v_fma_f32 v94, -v135, v61, v94
	v_fma_f32 v94, -v144, v64, v94
	v_fma_f32 v94, -v145, v65, v94
	v_fma_f32 v94, -v146, v66, v94
	v_fma_f32 v94, -v147, v67, v94
	v_fma_f32 v94, -v148, v68, v94
	v_fma_f32 v94, -v149, v69, v94
	v_fma_f32 v94, -v150, v70, v94
	v_fma_f32 v94, -v151, v71, v94
	v_fma_f32 v94, -v152, v72, v94
	v_fma_f32 v94, -v153, v73, v94
	v_fma_f32 v94, -v154, v74, v94
	v_fma_f32 v94, -v155, v75, v94
	v_fma_f32 v94, -v2, v76, v94
	v_fma_f32 v94, -v3, v77, v94
	v_fma_f32 v94, -v4, v78, v94
	v_fma_f32 v94, -v5, v79, v94
	v_fma_f32 v94, -v10, v80, v94
	v_fma_f32 v94, -v11, v81, v94
	v_fma_f32 v94, -v12, v82, v94
	v_fma_f32 v94, -v13, v83, v94
	v_fma_f32 v94, -v14, v84, v94
	v_fma_f32 v94, -v15, v85, v94
	v_fma_f32 v94, -v16, v86, v94
	v_fma_f32 v94, -v17, v87, v94
	v_fma_f32 v94, -v18, v88, v94
	v_fma_f32 v94, -v19, v89, v94
	v_fma_f32 v94, -v20, v90, v94
	v_fma_f32 v94, -v21, v91, v94
	v_fma_f32 v94, -v22, v92, v94
	v_fma_f32 v94, -v23, v93, v94
	s_waitcnt lgkmcnt(7)
	v_fma_f32 v95, -v24, v45, v95
	ds_read_u16 v2, v63 offset:13056
	ds_read_b32 v3, v62 offset:192
	ds_read_b128 v[10:13], v57 offset:12912
	ds_read_b128 v[14:17], v57 offset:12928
	ds_read_b128 v[18:21], v57 offset:12944
	ds_read_b128 v[120:123], v57 offset:12960
	v_fma_f32 v95, -v25, v46, v95
	s_waitcnt lgkmcnt(5)
	v_lshlrev_b32_e32 v2, 16, v2
	v_fma_f32 v95, -v26, v47, v95
	s_waitcnt lgkmcnt(4)
	v_mul_f32_e32 v96, v3, v2
	v_fma_f32 v95, -v27, v48, v95
	ds_read_b128 v[124:127], v57 offset:13056
	ds_read_b128 v[128:131], v57 offset:13072
	ds_read_b128 v[132:135], v57 offset:13088
	ds_read_b128 v[144:147], v57 offset:13104
	ds_read_b128 v[148:151], v57 offset:13120
	ds_read_b128 v[152:155], v57 offset:13136
	ds_read_b128 v[156:159], v57 offset:13152
	ds_read_b128 v[2:5], v57 offset:13168
	v_fma_f32 v95, -v28, v49, v95
	v_fma_f32 v95, -v29, v50, v95
	v_fma_f32 v95, -v30, v51, v95
	v_fma_f32 v95, -v31, v52, v95
	v_fma_f32 v95, -v32, v53, v95
	v_fma_f32 v95, -v33, v54, v95
	v_fma_f32 v95, -v34, v55, v95
	v_fma_f32 v95, -v35, v56, v95
	v_fma_f32 v95, -v36, v58, v95
	v_fma_f32 v95, -v37, v59, v95
	v_fma_f32 v95, -v38, v60, v95
	v_fma_f32 v95, -v39, v61, v95
	v_fma_f32 v95, -v106, v64, v95
	v_fma_f32 v95, -v107, v65, v95
	v_fma_f32 v95, -v108, v66, v95
	v_fma_f32 v95, -v109, v67, v95
	v_fma_f32 v95, -v110, v68, v95
	v_fma_f32 v95, -v111, v69, v95
	v_fma_f32 v95, -v112, v70, v95
	v_fma_f32 v95, -v113, v71, v95
	v_fma_f32 v95, -v114, v72, v95
	v_fma_f32 v95, -v115, v73, v95
	v_fma_f32 v95, -v116, v74, v95
	v_fma_f32 v95, -v117, v75, v95
	v_fma_f32 v95, -v6, v76, v95
	v_fma_f32 v95, -v7, v77, v95
	v_fma_f32 v95, -v8, v78, v95
	v_fma_f32 v95, -v9, v79, v95
	s_waitcnt lgkmcnt(11)
	v_fma_f32 v95, -v10, v80, v95
	v_fma_f32 v95, -v11, v81, v95
	v_fma_f32 v95, -v12, v82, v95
	v_fma_f32 v95, -v13, v83, v95
	s_waitcnt lgkmcnt(10)
	v_fma_f32 v95, -v14, v84, v95
	v_fma_f32 v95, -v15, v85, v95
	v_fma_f32 v95, -v16, v86, v95
	v_fma_f32 v95, -v17, v87, v95
	s_waitcnt lgkmcnt(9)
	v_fma_f32 v95, -v18, v88, v95
	v_fma_f32 v95, -v19, v89, v95
	v_fma_f32 v95, -v20, v90, v95
	v_fma_f32 v95, -v21, v91, v95
	s_waitcnt lgkmcnt(8)
	v_fma_f32 v95, -v120, v92, v95
	v_fma_f32 v95, -v121, v93, v95
	v_fma_f32 v95, -v122, v94, v95
	s_waitcnt lgkmcnt(7)
	v_fma_f32 v96, -v124, v45, v96
	ds_read_u16 v6, v63 offset:13328
	ds_read_b32 v7, v62 offset:196
	ds_read_b128 v[10:13], v57 offset:13184
	ds_read_b128 v[18:21], v57 offset:13200
	ds_read_b128 v[22:25], v57 offset:13216
	ds_read_b128 v[26:29], v57 offset:13232
	v_fma_f32 v96, -v125, v46, v96
	s_waitcnt lgkmcnt(5)
	v_lshlrev_b32_e32 v6, 16, v6
	v_fma_f32 v96, -v126, v47, v96
	s_waitcnt lgkmcnt(4)
	v_mul_f32_e32 v97, v7, v6
	v_fma_f32 v96, -v127, v48, v96
	ds_read_b128 v[30:33], v57 offset:13328
	ds_read_b128 v[34:37], v57 offset:13344
	ds_read_b128 v[38:41], v57 offset:13360
	ds_read_b128 v[106:109], v57 offset:13376
	ds_read_b128 v[110:113], v57 offset:13392
	ds_read_b128 v[114:117], v57 offset:13408
	ds_read_b128 v[14:17], v57 offset:13424
	ds_read_b128 v[6:9], v57 offset:13440
	v_fma_f32 v96, -v128, v49, v96
	v_fma_f32 v96, -v129, v50, v96
	v_fma_f32 v96, -v130, v51, v96
	v_fma_f32 v96, -v131, v52, v96
	v_fma_f32 v96, -v132, v53, v96
	v_fma_f32 v96, -v133, v54, v96
	v_fma_f32 v96, -v134, v55, v96
	v_fma_f32 v96, -v135, v56, v96
	v_fma_f32 v96, -v144, v58, v96
	v_fma_f32 v96, -v145, v59, v96
	v_fma_f32 v96, -v146, v60, v96
	v_fma_f32 v96, -v147, v61, v96
	v_fma_f32 v96, -v148, v64, v96
	v_fma_f32 v96, -v149, v65, v96
	v_fma_f32 v96, -v150, v66, v96
	v_fma_f32 v96, -v151, v67, v96
	v_fma_f32 v96, -v152, v68, v96
	v_fma_f32 v96, -v153, v69, v96
	v_fma_f32 v96, -v154, v70, v96
	v_fma_f32 v96, -v155, v71, v96
	v_fma_f32 v96, -v156, v72, v96
	v_fma_f32 v96, -v157, v73, v96
	v_fma_f32 v96, -v158, v74, v96
	v_fma_f32 v96, -v159, v75, v96
	v_fma_f32 v96, -v2, v76, v96
	v_fma_f32 v96, -v3, v77, v96
	v_fma_f32 v96, -v4, v78, v96
	v_fma_f32 v96, -v5, v79, v96
	s_waitcnt lgkmcnt(11)
	v_fma_f32 v96, -v10, v80, v96
	v_fma_f32 v96, -v11, v81, v96
	v_fma_f32 v96, -v12, v82, v96
	v_fma_f32 v96, -v13, v83, v96
	s_waitcnt lgkmcnt(10)
	v_fma_f32 v96, -v18, v84, v96
	v_fma_f32 v96, -v19, v85, v96
	v_fma_f32 v96, -v20, v86, v96
	v_fma_f32 v96, -v21, v87, v96
	s_waitcnt lgkmcnt(9)
	v_fma_f32 v96, -v22, v88, v96
	v_fma_f32 v96, -v23, v89, v96
	v_fma_f32 v96, -v24, v90, v96
	v_fma_f32 v96, -v25, v91, v96
	s_waitcnt lgkmcnt(8)
	v_fma_f32 v96, -v26, v92, v96
	v_fma_f32 v96, -v27, v93, v96
	v_fma_f32 v96, -v28, v94, v96
	v_fma_f32 v96, -v29, v95, v96
	s_waitcnt lgkmcnt(7)
	v_fma_f32 v97, -v30, v45, v97
	ds_read_u16 v2, v63 offset:13600
	ds_read_b32 v3, v62 offset:200
	ds_read_b128 v[18:21], v57 offset:13456
	ds_read_b128 v[22:25], v57 offset:13472
	ds_read_b128 v[26:29], v57 offset:13488
	ds_read_b128 v[120:123], v57 offset:13504
	v_fma_f32 v97, -v31, v46, v97
	s_waitcnt lgkmcnt(5)
	v_lshlrev_b32_e32 v2, 16, v2
	v_fma_f32 v97, -v32, v47, v97
	ds_read_b128 v[124:127], v57 offset:13520
	v_fma_f32 v97, -v33, v48, v97
	s_waitcnt lgkmcnt(5)
	v_mul_f32_e32 v98, v3, v2
	v_fma_f32 v97, -v34, v49, v97
	s_waitcnt lgkmcnt(0)
	ds_read_b128 v[126:129], v57 offset:13600
	ds_read_b128 v[130:133], v57 offset:13616
	ds_read_b128 v[144:147], v57 offset:13632
	ds_read_b128 v[148:151], v57 offset:13648
	ds_read_b128 v[152:155], v57 offset:13664
	ds_read_b128 v[156:159], v57 offset:13680
	ds_read_b128 v[10:13], v57 offset:13696
	ds_read_b128 v[2:5], v57 offset:13712
	v_fma_f32 v97, -v35, v50, v97
	v_fma_f32 v97, -v36, v51, v97
	v_fma_f32 v97, -v37, v52, v97
	v_fma_f32 v97, -v38, v53, v97
	v_fma_f32 v97, -v39, v54, v97
	v_fma_f32 v97, -v40, v55, v97
	v_fma_f32 v97, -v41, v56, v97
	v_fma_f32 v97, -v106, v58, v97
	v_fma_f32 v97, -v107, v59, v97
	v_fma_f32 v97, -v108, v60, v97
	v_fma_f32 v97, -v109, v61, v97
	v_fma_f32 v97, -v110, v64, v97
	v_fma_f32 v97, -v111, v65, v97
	v_fma_f32 v97, -v112, v66, v97
	v_fma_f32 v97, -v113, v67, v97
	v_fma_f32 v97, -v114, v68, v97
	v_fma_f32 v97, -v115, v69, v97
	v_fma_f32 v97, -v116, v70, v97
	v_fma_f32 v97, -v117, v71, v97
	v_fma_f32 v97, -v14, v72, v97
	v_fma_f32 v97, -v15, v73, v97
	v_fma_f32 v97, -v16, v74, v97
	v_fma_f32 v97, -v17, v75, v97
	v_fma_f32 v97, -v6, v76, v97
	v_fma_f32 v97, -v7, v77, v97
	v_fma_f32 v97, -v8, v78, v97
	v_fma_f32 v97, -v9, v79, v97
	v_fma_f32 v97, -v18, v80, v97
	v_fma_f32 v97, -v19, v81, v97
	v_fma_f32 v97, -v20, v82, v97
	v_fma_f32 v97, -v21, v83, v97
	v_fma_f32 v97, -v22, v84, v97
	v_fma_f32 v97, -v23, v85, v97
	v_fma_f32 v97, -v24, v86, v97
	v_fma_f32 v97, -v25, v87, v97
	v_fma_f32 v97, -v26, v88, v97
	v_fma_f32 v97, -v27, v89, v97
	v_fma_f32 v97, -v28, v90, v97
	v_fma_f32 v97, -v29, v91, v97
	v_fma_f32 v97, -v120, v92, v97
	v_fma_f32 v97, -v121, v93, v97
	v_fma_f32 v97, -v122, v94, v97
	v_fma_f32 v97, -v123, v95, v97
	v_fma_f32 v97, -v124, v96, v97
	s_waitcnt lgkmcnt(7)
	v_fma_f32 v98, -v126, v45, v98
	ds_read_u16 v6, v63 offset:13872
	ds_read_b32 v7, v62 offset:204
	ds_read_b128 v[18:21], v57 offset:13728
	ds_read_b128 v[22:25], v57 offset:13744
	ds_read_b128 v[26:29], v57 offset:13760
	ds_read_b128 v[30:33], v57 offset:13776
	v_fma_f32 v98, -v127, v46, v98
	s_waitcnt lgkmcnt(5)
	v_lshlrev_b32_e32 v6, 16, v6
	v_fma_f32 v98, -v128, v47, v98
	ds_read_b128 v[34:37], v57 offset:13792
	v_fma_f32 v98, -v129, v48, v98
	s_waitcnt lgkmcnt(5)
	v_mul_f32_e32 v103, v7, v6
	v_fma_f32 v98, -v130, v49, v98
	s_waitcnt lgkmcnt(0)
	ds_read_b128 v[36:39], v57 offset:13872
	ds_read_b128 v[108:111], v57 offset:13888
	ds_read_b128 v[112:115], v57 offset:13904
	ds_read_b128 v[120:123], v57 offset:13920
	ds_read_b128 v[180:183], v57 offset:13936
	ds_read_b128 v[184:187], v57 offset:13952
	ds_read_b128 v[14:17], v57 offset:13968
	ds_read_b128 v[6:9], v57 offset:13984
	v_fma_f32 v98, -v131, v50, v98
	v_fma_f32 v98, -v132, v51, v98
	v_fma_f32 v98, -v133, v52, v98
	v_fma_f32 v98, -v144, v53, v98
	v_fma_f32 v98, -v145, v54, v98
	v_fma_f32 v98, -v146, v55, v98
	v_fma_f32 v98, -v147, v56, v98
	v_fma_f32 v98, -v148, v58, v98
	v_fma_f32 v98, -v149, v59, v98
	v_fma_f32 v98, -v150, v60, v98
	v_fma_f32 v98, -v151, v61, v98
	v_fma_f32 v98, -v152, v64, v98
	v_fma_f32 v98, -v153, v65, v98
	v_fma_f32 v98, -v154, v66, v98
	v_fma_f32 v98, -v155, v67, v98
	v_fma_f32 v98, -v156, v68, v98
	v_fma_f32 v98, -v157, v69, v98
	v_fma_f32 v98, -v158, v70, v98
	v_fma_f32 v98, -v159, v71, v98
	v_fma_f32 v98, -v10, v72, v98
	v_fma_f32 v98, -v11, v73, v98
	v_fma_f32 v98, -v12, v74, v98
	v_fma_f32 v98, -v13, v75, v98
	v_fma_f32 v98, -v2, v76, v98
	v_fma_f32 v98, -v3, v77, v98
	v_fma_f32 v98, -v4, v78, v98
	v_fma_f32 v98, -v5, v79, v98
	v_fma_f32 v98, -v18, v80, v98
	v_fma_f32 v98, -v19, v81, v98
	v_fma_f32 v98, -v20, v82, v98
	v_fma_f32 v98, -v21, v83, v98
	v_fma_f32 v98, -v22, v84, v98
	v_fma_f32 v98, -v23, v85, v98
	v_fma_f32 v98, -v24, v86, v98
	v_fma_f32 v98, -v25, v87, v98
	v_fma_f32 v98, -v26, v88, v98
	v_fma_f32 v98, -v27, v89, v98
	v_fma_f32 v98, -v28, v90, v98
	v_fma_f32 v98, -v29, v91, v98
	v_fma_f32 v98, -v30, v92, v98
	v_fma_f32 v98, -v31, v93, v98
	v_fma_f32 v98, -v32, v94, v98
	v_fma_f32 v98, -v33, v95, v98
	v_fma_f32 v98, -v34, v96, v98
	v_fma_f32 v98, -v35, v97, v98
	s_waitcnt lgkmcnt(7)
	v_fma_f32 v103, -v36, v45, v103
	ds_read_u16 v2, v63 offset:14144
	ds_read_b32 v3, v62 offset:208
	ds_read_b128 v[18:21], v57 offset:14000
	ds_read_b128 v[22:25], v57 offset:14016
	ds_read_b128 v[26:29], v57 offset:14032
	ds_read_b128 v[30:33], v57 offset:14048
	v_fma_f32 v103, -v37, v46, v103
	s_waitcnt lgkmcnt(5)
	v_lshlrev_b32_e32 v2, 16, v2
	v_fma_f32 v103, -v38, v47, v103
	s_waitcnt lgkmcnt(4)
	v_mul_f32_e32 v106, v3, v2
	v_fma_f32 v103, -v39, v48, v103
	ds_read_b128 v[124:127], v57 offset:14064
	ds_read_b128 v[128:131], v57 offset:14144
	ds_read_b128 v[132:135], v57 offset:14160
	ds_read_b128 v[144:147], v57 offset:14176
	ds_read_b128 v[148:151], v57 offset:14192
	ds_read_b128 v[152:155], v57 offset:14208
	ds_read_b128 v[156:159], v57 offset:14224
	ds_read_b128 v[10:13], v57 offset:14240
	ds_read_b128 v[2:5], v57 offset:14256
	v_fma_f32 v103, -v108, v49, v103
	v_fma_f32 v103, -v109, v50, v103
	v_fma_f32 v103, -v110, v51, v103
	v_fma_f32 v103, -v111, v52, v103
	v_fma_f32 v103, -v112, v53, v103
	v_fma_f32 v103, -v113, v54, v103
	v_fma_f32 v103, -v114, v55, v103
	v_fma_f32 v103, -v115, v56, v103
	v_fma_f32 v103, -v120, v58, v103
	v_fma_f32 v103, -v121, v59, v103
	v_fma_f32 v103, -v122, v60, v103
	v_fma_f32 v103, -v123, v61, v103
	v_fma_f32 v103, -v180, v64, v103
	v_fma_f32 v103, -v181, v65, v103
	v_fma_f32 v103, -v182, v66, v103
	v_fma_f32 v103, -v183, v67, v103
	v_fma_f32 v103, -v184, v68, v103
	v_fma_f32 v103, -v185, v69, v103
	v_fma_f32 v103, -v186, v70, v103
	v_fma_f32 v103, -v187, v71, v103
	v_fma_f32 v103, -v14, v72, v103
	v_fma_f32 v103, -v15, v73, v103
	v_fma_f32 v103, -v16, v74, v103
	v_fma_f32 v103, -v17, v75, v103
	v_fma_f32 v103, -v6, v76, v103
	v_fma_f32 v103, -v7, v77, v103
	v_fma_f32 v103, -v8, v78, v103
	v_fma_f32 v103, -v9, v79, v103
	s_waitcnt lgkmcnt(12)
	v_fma_f32 v103, -v18, v80, v103
	v_fma_f32 v103, -v19, v81, v103
	v_fma_f32 v103, -v20, v82, v103
	v_fma_f32 v103, -v21, v83, v103
	s_waitcnt lgkmcnt(11)
	v_fma_f32 v103, -v22, v84, v103
	v_fma_f32 v103, -v23, v85, v103
	v_fma_f32 v103, -v24, v86, v103
	v_fma_f32 v103, -v25, v87, v103
	s_waitcnt lgkmcnt(10)
	v_fma_f32 v103, -v26, v88, v103
	v_fma_f32 v103, -v27, v89, v103
	v_fma_f32 v103, -v28, v90, v103
	v_fma_f32 v103, -v29, v91, v103
	s_waitcnt lgkmcnt(9)
	v_fma_f32 v103, -v30, v92, v103
	v_fma_f32 v103, -v31, v93, v103
	v_fma_f32 v103, -v32, v94, v103
	v_fma_f32 v103, -v33, v95, v103
	s_waitcnt lgkmcnt(8)
	v_fma_f32 v103, -v124, v96, v103
	v_fma_f32 v103, -v125, v97, v103
	v_fma_f32 v103, -v126, v98, v103
	s_waitcnt lgkmcnt(7)
	v_fma_f32 v106, -v128, v45, v106
	ds_read_u16 v6, v63 offset:14416
	ds_read_b32 v7, v62 offset:212
	ds_read_b128 v[18:21], v57 offset:14272
	ds_read_b128 v[26:29], v57 offset:14288
	ds_read_b128 v[30:33], v57 offset:14304
	ds_read_b128 v[34:37], v57 offset:14320
	v_fma_f32 v106, -v129, v46, v106
	s_waitcnt lgkmcnt(5)
	v_lshlrev_b32_e32 v6, 16, v6
	v_fma_f32 v106, -v130, v47, v106
	s_waitcnt lgkmcnt(4)
	v_mul_f32_e32 v107, v7, v6
	v_fma_f32 v106, -v131, v48, v106
	ds_read_b128 v[38:41], v57 offset:14336
	ds_read_b128 v[110:113], v57 offset:14416
	ds_read_b128 v[114:117], v57 offset:14432
	ds_read_b128 v[120:123], v57 offset:14448
	ds_read_b128 v[124:127], v57 offset:14464
	ds_read_b128 v[180:183], v57 offset:14480
	ds_read_b128 v[22:25], v57 offset:14496
	ds_read_b128 v[14:17], v57 offset:14512
	ds_read_b128 v[6:9], v57 offset:14528
	v_fma_f32 v106, -v132, v49, v106
	v_fma_f32 v106, -v133, v50, v106
	v_fma_f32 v106, -v134, v51, v106
	v_fma_f32 v106, -v135, v52, v106
	v_fma_f32 v106, -v144, v53, v106
	v_fma_f32 v106, -v145, v54, v106
	v_fma_f32 v106, -v146, v55, v106
	v_fma_f32 v106, -v147, v56, v106
	v_fma_f32 v106, -v148, v58, v106
	v_fma_f32 v106, -v149, v59, v106
	v_fma_f32 v106, -v150, v60, v106
	v_fma_f32 v106, -v151, v61, v106
	v_fma_f32 v106, -v152, v64, v106
	v_fma_f32 v106, -v153, v65, v106
	v_fma_f32 v106, -v154, v66, v106
	v_fma_f32 v106, -v155, v67, v106
	v_fma_f32 v106, -v156, v68, v106
	v_fma_f32 v106, -v157, v69, v106
	v_fma_f32 v106, -v158, v70, v106
	v_fma_f32 v106, -v159, v71, v106
	v_fma_f32 v106, -v10, v72, v106
	v_fma_f32 v106, -v11, v73, v106
	v_fma_f32 v106, -v12, v74, v106
	v_fma_f32 v106, -v13, v75, v106
	v_fma_f32 v106, -v2, v76, v106
	v_fma_f32 v106, -v3, v77, v106
	v_fma_f32 v106, -v4, v78, v106
	v_fma_f32 v106, -v5, v79, v106
	s_waitcnt lgkmcnt(12)
	v_fma_f32 v106, -v18, v80, v106
	v_fma_f32 v106, -v19, v81, v106
	v_fma_f32 v106, -v20, v82, v106
	v_fma_f32 v106, -v21, v83, v106
	s_waitcnt lgkmcnt(11)
	v_fma_f32 v106, -v26, v84, v106
	v_fma_f32 v106, -v27, v85, v106
	v_fma_f32 v106, -v28, v86, v106
	v_fma_f32 v106, -v29, v87, v106
	s_waitcnt lgkmcnt(10)
	v_fma_f32 v106, -v30, v88, v106
	v_fma_f32 v106, -v31, v89, v106
	v_fma_f32 v106, -v32, v90, v106
	v_fma_f32 v106, -v33, v91, v106
	s_waitcnt lgkmcnt(9)
	v_fma_f32 v106, -v34, v92, v106
	v_fma_f32 v106, -v35, v93, v106
	v_fma_f32 v106, -v36, v94, v106
	v_fma_f32 v106, -v37, v95, v106
	s_waitcnt lgkmcnt(8)
	v_fma_f32 v106, -v38, v96, v106
	v_fma_f32 v106, -v39, v97, v106
	v_fma_f32 v106, -v40, v98, v106
	v_fma_f32 v106, -v41, v103, v106
	s_waitcnt lgkmcnt(7)
	v_fma_f32 v107, -v110, v45, v107
	ds_read_b128 v[26:29], v57 offset:14544
	ds_read_b128 v[30:33], v57 offset:14560
	ds_read_u16 v2, v63 offset:14688
	ds_read_b32 v3, v62 offset:216
	ds_read_b128 v[34:37], v57 offset:14576
	ds_read_b128 v[38:41], v57 offset:14592
	ds_read_b128 v[128:131], v57 offset:14608
	ds_read_b128 v[132:135], v57 offset:14624
	v_fma_f32 v107, -v111, v46, v107
	s_waitcnt lgkmcnt(5)
	v_lshlrev_b32_e32 v2, 16, v2
	v_fma_f32 v107, -v112, v47, v107
	s_waitcnt lgkmcnt(4)
	v_mul_f32_e32 v108, v3, v2
	v_fma_f32 v107, -v113, v48, v107
	ds_read_b128 v[144:147], v57 offset:14688
	ds_read_b128 v[148:151], v57 offset:14704
	ds_read_b128 v[152:155], v57 offset:14720
	ds_read_b128 v[156:159], v57 offset:14736
	ds_read_b128 v[184:187], v57 offset:14752
	ds_read_b128 v[18:21], v57 offset:14768
	ds_read_b128 v[10:13], v57 offset:14784
	ds_read_b128 v[2:5], v57 offset:14800
	v_fma_f32 v107, -v114, v49, v107
	v_fma_f32 v107, -v115, v50, v107
	v_fma_f32 v107, -v116, v51, v107
	v_fma_f32 v107, -v117, v52, v107
	v_fma_f32 v107, -v120, v53, v107
	v_fma_f32 v107, -v121, v54, v107
	v_fma_f32 v107, -v122, v55, v107
	v_fma_f32 v107, -v123, v56, v107
	v_fma_f32 v107, -v124, v58, v107
	v_fma_f32 v107, -v125, v59, v107
	v_fma_f32 v107, -v126, v60, v107
	v_fma_f32 v107, -v127, v61, v107
	v_fma_f32 v107, -v180, v64, v107
	v_fma_f32 v107, -v181, v65, v107
	v_fma_f32 v107, -v182, v66, v107
	v_fma_f32 v107, -v183, v67, v107
	v_fma_f32 v107, -v22, v68, v107
	v_fma_f32 v107, -v23, v69, v107
	v_fma_f32 v107, -v24, v70, v107
	v_fma_f32 v107, -v25, v71, v107
	v_fma_f32 v107, -v14, v72, v107
	v_fma_f32 v107, -v15, v73, v107
	v_fma_f32 v107, -v16, v74, v107
	v_fma_f32 v107, -v17, v75, v107
	v_fma_f32 v107, -v6, v76, v107
	v_fma_f32 v107, -v7, v77, v107
	v_fma_f32 v107, -v8, v78, v107
	v_fma_f32 v107, -v9, v79, v107
	v_fma_f32 v107, -v26, v80, v107
	v_fma_f32 v107, -v27, v81, v107
	v_fma_f32 v107, -v28, v82, v107
	v_fma_f32 v107, -v29, v83, v107
	v_fma_f32 v107, -v30, v84, v107
	v_fma_f32 v107, -v31, v85, v107
	v_fma_f32 v107, -v32, v86, v107
	v_fma_f32 v107, -v33, v87, v107
	s_waitcnt lgkmcnt(11)
	v_fma_f32 v107, -v34, v88, v107
	v_fma_f32 v107, -v35, v89, v107
	v_fma_f32 v107, -v36, v90, v107
	v_fma_f32 v107, -v37, v91, v107
	s_waitcnt lgkmcnt(10)
	v_fma_f32 v107, -v38, v92, v107
	v_fma_f32 v107, -v39, v93, v107
	v_fma_f32 v107, -v40, v94, v107
	v_fma_f32 v107, -v41, v95, v107
	s_waitcnt lgkmcnt(9)
	v_fma_f32 v107, -v128, v96, v107
	v_fma_f32 v107, -v129, v97, v107
	v_fma_f32 v107, -v130, v98, v107
	v_fma_f32 v107, -v131, v103, v107
	s_waitcnt lgkmcnt(8)
	v_fma_f32 v107, -v132, v106, v107
	s_waitcnt lgkmcnt(7)
	v_fma_f32 v108, -v144, v45, v108
	ds_read_b128 v[26:29], v57 offset:14816
	ds_read_b128 v[30:33], v57 offset:14832
	ds_read_u16 v6, v63 offset:14960
	ds_read_b32 v7, v62 offset:220
	ds_read_b128 v[34:37], v57 offset:14848
	ds_read_b128 v[38:41], v57 offset:14864
	ds_read_b128 v[110:113], v57 offset:14880
	ds_read_b128 v[114:117], v57 offset:14896
	v_fma_f32 v108, -v145, v46, v108
	s_waitcnt lgkmcnt(5)
	v_lshlrev_b32_e32 v6, 16, v6
	v_fma_f32 v108, -v146, v47, v108
	s_waitcnt lgkmcnt(4)
	v_mul_f32_e32 v109, v7, v6
	v_fma_f32 v108, -v147, v48, v108
	ds_read_b128 v[120:123], v57 offset:14960
	ds_read_b128 v[124:127], v57 offset:14976
	ds_read_b128 v[128:131], v57 offset:14992
	ds_read_b128 v[132:135], v57 offset:15008
	ds_read_b128 v[180:183], v57 offset:15024
	ds_read_b128 v[22:25], v57 offset:15040
	ds_read_b128 v[14:17], v57 offset:15056
	ds_read_b128 v[6:9], v57 offset:15072
	v_fma_f32 v108, -v148, v49, v108
	v_fma_f32 v108, -v149, v50, v108
	v_fma_f32 v108, -v150, v51, v108
	v_fma_f32 v108, -v151, v52, v108
	v_fma_f32 v108, -v152, v53, v108
	v_fma_f32 v108, -v153, v54, v108
	v_fma_f32 v108, -v154, v55, v108
	v_fma_f32 v108, -v155, v56, v108
	v_fma_f32 v108, -v156, v58, v108
	v_fma_f32 v108, -v157, v59, v108
	v_fma_f32 v108, -v158, v60, v108
	v_fma_f32 v108, -v159, v61, v108
	v_fma_f32 v108, -v184, v64, v108
	v_fma_f32 v108, -v185, v65, v108
	v_fma_f32 v108, -v186, v66, v108
	v_fma_f32 v108, -v187, v67, v108
	v_fma_f32 v108, -v18, v68, v108
	v_fma_f32 v108, -v19, v69, v108
	v_fma_f32 v108, -v20, v70, v108
	v_fma_f32 v108, -v21, v71, v108
	v_fma_f32 v108, -v10, v72, v108
	v_fma_f32 v108, -v11, v73, v108
	v_fma_f32 v108, -v12, v74, v108
	v_fma_f32 v108, -v13, v75, v108
	v_fma_f32 v108, -v2, v76, v108
	v_fma_f32 v108, -v3, v77, v108
	v_fma_f32 v108, -v4, v78, v108
	v_fma_f32 v108, -v5, v79, v108
	v_fma_f32 v108, -v26, v80, v108
	v_fma_f32 v108, -v27, v81, v108
	v_fma_f32 v108, -v28, v82, v108
	v_fma_f32 v108, -v29, v83, v108
	v_fma_f32 v108, -v30, v84, v108
	v_fma_f32 v108, -v31, v85, v108
	v_fma_f32 v108, -v32, v86, v108
	v_fma_f32 v108, -v33, v87, v108
	s_waitcnt lgkmcnt(11)
	v_fma_f32 v108, -v34, v88, v108
	v_fma_f32 v108, -v35, v89, v108
	v_fma_f32 v108, -v36, v90, v108
	v_fma_f32 v108, -v37, v91, v108
	s_waitcnt lgkmcnt(10)
	v_fma_f32 v108, -v38, v92, v108
	v_fma_f32 v108, -v39, v93, v108
	v_fma_f32 v108, -v40, v94, v108
	v_fma_f32 v108, -v41, v95, v108
	s_waitcnt lgkmcnt(9)
	v_fma_f32 v108, -v110, v96, v108
	v_fma_f32 v108, -v111, v97, v108
	v_fma_f32 v108, -v112, v98, v108
	v_fma_f32 v108, -v113, v103, v108
	s_waitcnt lgkmcnt(8)
	v_fma_f32 v108, -v114, v106, v108
	v_fma_f32 v108, -v115, v107, v108
	s_waitcnt lgkmcnt(7)
	v_fma_f32 v109, -v120, v45, v109
	ds_read_b128 v[30:33], v57 offset:15088
	ds_read_b128 v[34:37], v57 offset:15104
	ds_read_u16 v2, v63 offset:15232
	ds_read_b32 v3, v62 offset:224
	ds_read_b128 v[38:41], v57 offset:15120
	ds_read_b128 v[112:115], v57 offset:15136
	ds_read_b128 v[144:147], v57 offset:15152
	ds_read_b128 v[148:151], v57 offset:15168
	v_fma_f32 v109, -v121, v46, v109
	s_waitcnt lgkmcnt(5)
	v_lshlrev_b32_e32 v2, 16, v2
	v_fma_f32 v109, -v122, v47, v109
	s_waitcnt lgkmcnt(4)
	v_mul_f32_e32 v110, v3, v2
	v_fma_f32 v109, -v123, v48, v109
	ds_read_b128 v[152:155], v57 offset:15232
	ds_read_b128 v[156:159], v57 offset:15248
	ds_read_b128 v[184:187], v57 offset:15264
	ds_read_b128 v[188:191], v57 offset:15280
	ds_read_b128 v[26:29], v57 offset:15296
	ds_read_b128 v[18:21], v57 offset:15312
	ds_read_b128 v[10:13], v57 offset:15328
	ds_read_b128 v[2:5], v57 offset:15344
	v_fma_f32 v109, -v124, v49, v109
	v_fma_f32 v109, -v125, v50, v109
	v_fma_f32 v109, -v126, v51, v109
	v_fma_f32 v109, -v127, v52, v109
	v_fma_f32 v109, -v128, v53, v109
	v_fma_f32 v109, -v129, v54, v109
	v_fma_f32 v109, -v130, v55, v109
	v_fma_f32 v109, -v131, v56, v109
	v_fma_f32 v109, -v132, v58, v109
	v_fma_f32 v109, -v133, v59, v109
	v_fma_f32 v109, -v134, v60, v109
	v_fma_f32 v109, -v135, v61, v109
	v_fma_f32 v109, -v180, v64, v109
	v_fma_f32 v109, -v181, v65, v109
	v_fma_f32 v109, -v182, v66, v109
	v_fma_f32 v109, -v183, v67, v109
	v_fma_f32 v109, -v22, v68, v109
	v_fma_f32 v109, -v23, v69, v109
	v_fma_f32 v109, -v24, v70, v109
	v_fma_f32 v109, -v25, v71, v109
	v_fma_f32 v109, -v14, v72, v109
	v_fma_f32 v109, -v15, v73, v109
	v_fma_f32 v109, -v16, v74, v109
	v_fma_f32 v109, -v17, v75, v109
	v_fma_f32 v109, -v6, v76, v109
	v_fma_f32 v109, -v7, v77, v109
	v_fma_f32 v109, -v8, v78, v109
	v_fma_f32 v109, -v9, v79, v109
	v_fma_f32 v109, -v30, v80, v109
	v_fma_f32 v109, -v31, v81, v109
	v_fma_f32 v109, -v32, v82, v109
	v_fma_f32 v109, -v33, v83, v109
	v_fma_f32 v109, -v34, v84, v109
	v_fma_f32 v109, -v35, v85, v109
	v_fma_f32 v109, -v36, v86, v109
	v_fma_f32 v109, -v37, v87, v109
	s_waitcnt lgkmcnt(11)
	v_fma_f32 v109, -v38, v88, v109
	v_fma_f32 v109, -v39, v89, v109
	v_fma_f32 v109, -v40, v90, v109
	v_fma_f32 v109, -v41, v91, v109
	s_waitcnt lgkmcnt(10)
	v_fma_f32 v109, -v112, v92, v109
	v_fma_f32 v109, -v113, v93, v109
	v_fma_f32 v109, -v114, v94, v109
	v_fma_f32 v109, -v115, v95, v109
	s_waitcnt lgkmcnt(9)
	v_fma_f32 v109, -v144, v96, v109
	v_fma_f32 v109, -v145, v97, v109
	v_fma_f32 v109, -v146, v98, v109
	v_fma_f32 v109, -v147, v103, v109
	s_waitcnt lgkmcnt(8)
	v_fma_f32 v109, -v148, v106, v109
	v_fma_f32 v109, -v149, v107, v109
	v_fma_f32 v109, -v150, v108, v109
	s_waitcnt lgkmcnt(7)
	v_fma_f32 v110, -v152, v45, v110
	ds_read_b128 v[34:37], v57 offset:15360
	ds_read_b128 v[38:41], v57 offset:15376
	ds_read_u16 v6, v63 offset:15504
	ds_read_b32 v7, v62 offset:228
	ds_read_b128 v[112:115], v57 offset:15392
	ds_read_b128 v[120:123], v57 offset:15408
	ds_read_b128 v[124:127], v57 offset:15424
	ds_read_b128 v[128:131], v57 offset:15440
	v_fma_f32 v110, -v153, v46, v110
	s_waitcnt lgkmcnt(5)
	v_lshlrev_b32_e32 v6, 16, v6
	v_fma_f32 v110, -v154, v47, v110
	s_waitcnt lgkmcnt(4)
	v_mul_f32_e32 v111, v7, v6
	v_fma_f32 v110, -v155, v48, v110
	ds_read_b128 v[132:135], v57 offset:15504
	ds_read_b128 v[144:147], v57 offset:15520
	ds_read_b128 v[148:151], v57 offset:15536
	ds_read_b128 v[180:183], v57 offset:15552
	ds_read_b128 v[30:33], v57 offset:15568
	ds_read_b128 v[22:25], v57 offset:15584
	ds_read_b128 v[14:17], v57 offset:15600
	ds_read_b128 v[6:9], v57 offset:15616
	v_fma_f32 v110, -v156, v49, v110
	v_fma_f32 v110, -v157, v50, v110
	v_fma_f32 v110, -v158, v51, v110
	v_fma_f32 v110, -v159, v52, v110
	v_fma_f32 v110, -v184, v53, v110
	v_fma_f32 v110, -v185, v54, v110
	v_fma_f32 v110, -v186, v55, v110
	v_fma_f32 v110, -v187, v56, v110
	v_fma_f32 v110, -v188, v58, v110
	v_fma_f32 v110, -v189, v59, v110
	v_fma_f32 v110, -v190, v60, v110
	v_fma_f32 v110, -v191, v61, v110
	v_fma_f32 v110, -v26, v64, v110
	v_fma_f32 v110, -v27, v65, v110
	v_fma_f32 v110, -v28, v66, v110
	v_fma_f32 v110, -v29, v67, v110
	v_fma_f32 v110, -v18, v68, v110
	v_fma_f32 v110, -v19, v69, v110
	v_fma_f32 v110, -v20, v70, v110
	v_fma_f32 v110, -v21, v71, v110
	v_fma_f32 v110, -v10, v72, v110
	v_fma_f32 v110, -v11, v73, v110
	v_fma_f32 v110, -v12, v74, v110
	v_fma_f32 v110, -v13, v75, v110
	v_fma_f32 v110, -v2, v76, v110
	v_fma_f32 v110, -v3, v77, v110
	v_fma_f32 v110, -v4, v78, v110
	v_fma_f32 v110, -v5, v79, v110
	v_fma_f32 v110, -v34, v80, v110
	v_fma_f32 v110, -v35, v81, v110
	v_fma_f32 v110, -v36, v82, v110
	v_fma_f32 v110, -v37, v83, v110
	v_fma_f32 v110, -v38, v84, v110
	v_fma_f32 v110, -v39, v85, v110
	v_fma_f32 v110, -v40, v86, v110
	v_fma_f32 v110, -v41, v87, v110
	s_waitcnt lgkmcnt(11)
	v_fma_f32 v110, -v112, v88, v110
	v_fma_f32 v110, -v113, v89, v110
	v_fma_f32 v110, -v114, v90, v110
	v_fma_f32 v110, -v115, v91, v110
	s_waitcnt lgkmcnt(10)
	v_fma_f32 v110, -v120, v92, v110
	v_fma_f32 v110, -v121, v93, v110
	v_fma_f32 v110, -v122, v94, v110
	v_fma_f32 v110, -v123, v95, v110
	s_waitcnt lgkmcnt(9)
	v_fma_f32 v110, -v124, v96, v110
	v_fma_f32 v110, -v125, v97, v110
	v_fma_f32 v110, -v126, v98, v110
	v_fma_f32 v110, -v127, v103, v110
	s_waitcnt lgkmcnt(8)
	v_fma_f32 v110, -v128, v106, v110
	v_fma_f32 v110, -v129, v107, v110
	v_fma_f32 v110, -v130, v108, v110
	v_fma_f32 v110, -v131, v109, v110
	s_waitcnt lgkmcnt(7)
	v_fma_f32 v111, -v132, v45, v111
	ds_read_b128 v[34:37], v57 offset:15632
	ds_read_b128 v[38:41], v57 offset:15648
	ds_read_u16 v2, v63 offset:15776
	ds_read_b32 v3, v62 offset:232
	ds_read_b128 v[114:117], v57 offset:15664
	ds_read_b128 v[120:123], v57 offset:15680
	ds_read_b128 v[124:127], v57 offset:15696
	ds_read_b128 v[128:131], v57 offset:15712
	v_fma_f32 v111, -v133, v46, v111
	s_waitcnt lgkmcnt(5)
	v_lshlrev_b32_e32 v2, 16, v2
	v_fma_f32 v111, -v134, v47, v111
	ds_read_b128 v[152:155], v57 offset:15728
	v_fma_f32 v111, -v135, v48, v111
	s_waitcnt lgkmcnt(5)
	v_mul_f32_e32 v112, v3, v2
	v_fma_f32 v111, -v144, v49, v111
	s_waitcnt lgkmcnt(0)
	ds_read_b128 v[154:157], v57 offset:15776
	ds_read_b128 v[158:161], v57 offset:15792
	ds_read_b128 v[184:187], v57 offset:15808
	ds_read_b128 v[188:191], v57 offset:15824
	ds_read_b128 v[26:29], v57 offset:15840
	ds_read_b128 v[18:21], v57 offset:15856
	ds_read_b128 v[10:13], v57 offset:15872
	ds_read_b128 v[2:5], v57 offset:15888
	v_fma_f32 v111, -v145, v50, v111
	v_fma_f32 v111, -v146, v51, v111
	v_fma_f32 v111, -v147, v52, v111
	v_fma_f32 v111, -v148, v53, v111
	v_fma_f32 v111, -v149, v54, v111
	v_fma_f32 v111, -v150, v55, v111
	v_fma_f32 v111, -v151, v56, v111
	v_fma_f32 v111, -v180, v58, v111
	v_fma_f32 v111, -v181, v59, v111
	v_fma_f32 v111, -v182, v60, v111
	v_fma_f32 v111, -v183, v61, v111
	v_fma_f32 v111, -v30, v64, v111
	v_fma_f32 v111, -v31, v65, v111
	v_fma_f32 v111, -v32, v66, v111
	v_fma_f32 v111, -v33, v67, v111
	v_fma_f32 v111, -v22, v68, v111
	v_fma_f32 v111, -v23, v69, v111
	v_fma_f32 v111, -v24, v70, v111
	v_fma_f32 v111, -v25, v71, v111
	v_fma_f32 v111, -v14, v72, v111
	v_fma_f32 v111, -v15, v73, v111
	v_fma_f32 v111, -v16, v74, v111
	v_fma_f32 v111, -v17, v75, v111
	v_fma_f32 v111, -v6, v76, v111
	v_fma_f32 v111, -v7, v77, v111
	v_fma_f32 v111, -v8, v78, v111
	v_fma_f32 v111, -v9, v79, v111
	v_fma_f32 v111, -v34, v80, v111
	v_fma_f32 v111, -v35, v81, v111
	v_fma_f32 v111, -v36, v82, v111
	v_fma_f32 v111, -v37, v83, v111
	v_fma_f32 v111, -v38, v84, v111
	v_fma_f32 v111, -v39, v85, v111
	v_fma_f32 v111, -v40, v86, v111
	v_fma_f32 v111, -v41, v87, v111
	v_fma_f32 v111, -v114, v88, v111
	v_fma_f32 v111, -v115, v89, v111
	v_fma_f32 v111, -v116, v90, v111
	v_fma_f32 v111, -v117, v91, v111
	v_fma_f32 v111, -v120, v92, v111
	v_fma_f32 v111, -v121, v93, v111
	v_fma_f32 v111, -v122, v94, v111
	v_fma_f32 v111, -v123, v95, v111
	v_fma_f32 v111, -v124, v96, v111
	v_fma_f32 v111, -v125, v97, v111
	v_fma_f32 v111, -v126, v98, v111
	v_fma_f32 v111, -v127, v103, v111
	v_fma_f32 v111, -v128, v106, v111
	v_fma_f32 v111, -v129, v107, v111
	v_fma_f32 v111, -v130, v108, v111
	v_fma_f32 v111, -v131, v109, v111
	v_fma_f32 v111, -v152, v110, v111
	s_waitcnt lgkmcnt(7)
	v_fma_f32 v112, -v154, v45, v112
	ds_read_b128 v[34:37], v57 offset:15904
	ds_read_b128 v[114:117], v57 offset:15920
	ds_read_u16 v6, v63 offset:16048
	ds_read_b32 v7, v62 offset:236
	ds_read_b128 v[120:123], v57 offset:15936
	ds_read_b128 v[124:127], v57 offset:15952
	ds_read_b128 v[128:131], v57 offset:15968
	ds_read_b128 v[132:135], v57 offset:15984
	v_fma_f32 v112, -v155, v46, v112
	s_waitcnt lgkmcnt(5)
	v_lshlrev_b32_e32 v6, 16, v6
	v_fma_f32 v112, -v156, v47, v112
	ds_read_b128 v[144:147], v57 offset:16000
	v_fma_f32 v112, -v157, v48, v112
	s_waitcnt lgkmcnt(5)
	v_mul_f32_e32 v113, v7, v6
	v_fma_f32 v112, -v158, v49, v112
	s_waitcnt lgkmcnt(0)
	ds_read_b128 v[146:149], v57 offset:16048
	ds_read_b128 v[150:153], v57 offset:16064
	ds_read_b128 v[180:183], v57 offset:16080
	ds_read_b128 v[38:41], v57 offset:16096
	ds_read_b128 v[30:33], v57 offset:16112
	ds_read_b128 v[22:25], v57 offset:16128
	ds_read_b128 v[14:17], v57 offset:16144
	ds_read_b128 v[6:9], v57 offset:16160
	v_fma_f32 v112, -v159, v50, v112
	v_fma_f32 v112, -v160, v51, v112
	v_fma_f32 v112, -v161, v52, v112
	v_fma_f32 v112, -v184, v53, v112
	v_fma_f32 v112, -v185, v54, v112
	v_fma_f32 v112, -v186, v55, v112
	v_fma_f32 v112, -v187, v56, v112
	v_fma_f32 v112, -v188, v58, v112
	v_fma_f32 v112, -v189, v59, v112
	v_fma_f32 v112, -v190, v60, v112
	v_fma_f32 v112, -v191, v61, v112
	v_fma_f32 v112, -v26, v64, v112
	v_fma_f32 v112, -v27, v65, v112
	v_fma_f32 v112, -v28, v66, v112
	v_fma_f32 v112, -v29, v67, v112
	v_fma_f32 v112, -v18, v68, v112
	v_fma_f32 v112, -v19, v69, v112
	v_fma_f32 v112, -v20, v70, v112
	v_fma_f32 v112, -v21, v71, v112
	v_fma_f32 v112, -v10, v72, v112
	v_fma_f32 v112, -v11, v73, v112
	v_fma_f32 v112, -v12, v74, v112
	v_fma_f32 v112, -v13, v75, v112
	v_fma_f32 v112, -v2, v76, v112
	v_fma_f32 v112, -v3, v77, v112
	v_fma_f32 v112, -v4, v78, v112
	v_fma_f32 v112, -v5, v79, v112
	v_fma_f32 v112, -v34, v80, v112
	v_fma_f32 v112, -v35, v81, v112
	v_fma_f32 v112, -v36, v82, v112
	v_fma_f32 v112, -v37, v83, v112
	v_fma_f32 v112, -v114, v84, v112
	v_fma_f32 v112, -v115, v85, v112
	v_fma_f32 v112, -v116, v86, v112
	v_fma_f32 v112, -v117, v87, v112
	v_fma_f32 v112, -v120, v88, v112
	v_fma_f32 v112, -v121, v89, v112
	v_fma_f32 v112, -v122, v90, v112
	v_fma_f32 v112, -v123, v91, v112
	v_fma_f32 v112, -v124, v92, v112
	v_fma_f32 v112, -v125, v93, v112
	v_fma_f32 v112, -v126, v94, v112
	v_fma_f32 v112, -v127, v95, v112
	v_fma_f32 v112, -v128, v96, v112
	v_fma_f32 v112, -v129, v97, v112
	v_fma_f32 v112, -v130, v98, v112
	v_fma_f32 v112, -v131, v103, v112
	v_fma_f32 v112, -v132, v106, v112
	v_fma_f32 v112, -v133, v107, v112
	v_fma_f32 v112, -v134, v108, v112
	v_fma_f32 v112, -v135, v109, v112
	v_fma_f32 v112, -v144, v110, v112
	v_fma_f32 v112, -v145, v111, v112
	s_waitcnt lgkmcnt(7)
	v_fma_f32 v113, -v146, v45, v113
	ds_read_b128 v[120:123], v57 offset:16176
	ds_read_b128 v[124:127], v57 offset:16192
	ds_read_u16 v2, v63 offset:16320
	ds_read_b32 v3, v62 offset:240
	ds_read_b128 v[128:131], v57 offset:16208
	ds_read_b128 v[132:135], v57 offset:16224
	ds_read_b128 v[154:157], v57 offset:16240
	ds_read_b128 v[158:161], v57 offset:16256
	v_fma_f32 v113, -v147, v46, v113
	s_waitcnt lgkmcnt(5)
	v_lshlrev_b32_e32 v2, 16, v2
	v_fma_f32 v113, -v148, v47, v113
	s_waitcnt lgkmcnt(4)
	v_mul_f32_e32 v114, v3, v2
	v_fma_f32 v113, -v149, v48, v113
	ds_read_b128 v[184:187], v57 offset:16272
	ds_read_b128 v[188:191], v57 offset:16320
	ds_read_b128 v[192:195], v57 offset:16336
	ds_read_b128 v[196:199], v57 offset:16352
	ds_read_b128 v[34:37], v57 offset:16368
	ds_read_b128 v[26:29], v57 offset:16384
	ds_read_b128 v[18:21], v57 offset:16400
	ds_read_b128 v[10:13], v57 offset:16416
	ds_read_b128 v[2:5], v57 offset:16432
	v_fma_f32 v113, -v150, v49, v113
	v_fma_f32 v113, -v151, v50, v113
	v_fma_f32 v113, -v152, v51, v113
	v_fma_f32 v113, -v153, v52, v113
	v_fma_f32 v113, -v180, v53, v113
	v_fma_f32 v113, -v181, v54, v113
	v_fma_f32 v113, -v182, v55, v113
	v_fma_f32 v113, -v183, v56, v113
	v_fma_f32 v113, -v38, v58, v113
	v_fma_f32 v113, -v39, v59, v113
	v_fma_f32 v113, -v40, v60, v113
	v_fma_f32 v113, -v41, v61, v113
	v_fma_f32 v113, -v30, v64, v113
	v_fma_f32 v113, -v31, v65, v113
	v_fma_f32 v113, -v32, v66, v113
	v_fma_f32 v113, -v33, v67, v113
	v_fma_f32 v113, -v22, v68, v113
	v_fma_f32 v113, -v23, v69, v113
	v_fma_f32 v113, -v24, v70, v113
	v_fma_f32 v113, -v25, v71, v113
	v_fma_f32 v113, -v14, v72, v113
	v_fma_f32 v113, -v15, v73, v113
	v_fma_f32 v113, -v16, v74, v113
	v_fma_f32 v113, -v17, v75, v113
	v_fma_f32 v113, -v6, v76, v113
	v_fma_f32 v113, -v7, v77, v113
	v_fma_f32 v113, -v8, v78, v113
	v_fma_f32 v113, -v9, v79, v113
	v_fma_f32 v113, -v120, v80, v113
	v_fma_f32 v113, -v121, v81, v113
	v_fma_f32 v113, -v122, v82, v113
	v_fma_f32 v113, -v123, v83, v113
	v_fma_f32 v113, -v124, v84, v113
	v_fma_f32 v113, -v125, v85, v113
	v_fma_f32 v113, -v126, v86, v113
	v_fma_f32 v113, -v127, v87, v113
	s_waitcnt lgkmcnt(12)
	v_fma_f32 v113, -v128, v88, v113
	v_fma_f32 v113, -v129, v89, v113
	v_fma_f32 v113, -v130, v90, v113
	v_fma_f32 v113, -v131, v91, v113
	s_waitcnt lgkmcnt(11)
	v_fma_f32 v113, -v132, v92, v113
	v_fma_f32 v113, -v133, v93, v113
	v_fma_f32 v113, -v134, v94, v113
	v_fma_f32 v113, -v135, v95, v113
	s_waitcnt lgkmcnt(10)
	v_fma_f32 v113, -v154, v96, v113
	v_fma_f32 v113, -v155, v97, v113
	v_fma_f32 v113, -v156, v98, v113
	v_fma_f32 v113, -v157, v103, v113
	s_waitcnt lgkmcnt(9)
	v_fma_f32 v113, -v158, v106, v113
	v_fma_f32 v113, -v159, v107, v113
	v_fma_f32 v113, -v160, v108, v113
	v_fma_f32 v113, -v161, v109, v113
	s_waitcnt lgkmcnt(8)
	v_fma_f32 v113, -v184, v110, v113
	v_fma_f32 v113, -v185, v111, v113
	v_fma_f32 v113, -v186, v112, v113
	s_waitcnt lgkmcnt(7)
	v_fma_f32 v114, -v188, v45, v114
	ds_read_b128 v[120:123], v57 offset:16448
	ds_read_b128 v[124:127], v57 offset:16464
	ds_read_u16 v6, v63 offset:16592
	ds_read_b32 v7, v62 offset:244
	ds_read_b128 v[128:131], v57 offset:16480
	ds_read_b128 v[132:135], v57 offset:16496
	ds_read_b128 v[144:147], v57 offset:16512
	ds_read_b128 v[148:151], v57 offset:16528
	v_fma_f32 v114, -v189, v46, v114
	s_waitcnt lgkmcnt(5)
	v_lshlrev_b32_e32 v6, 16, v6
	v_fma_f32 v114, -v190, v47, v114
	s_waitcnt lgkmcnt(4)
	v_mul_f32_e32 v115, v7, v6
	v_fma_f32 v114, -v191, v48, v114
	ds_read_b128 v[152:155], v57 offset:16544
	ds_read_b128 v[156:159], v57 offset:16592
	ds_read_b128 v[180:183], v57 offset:16608
	ds_read_b128 v[184:187], v57 offset:16624
	ds_read_b128 v[38:41], v57 offset:16640
	ds_read_b128 v[30:33], v57 offset:16656
	ds_read_b128 v[22:25], v57 offset:16672
	ds_read_b128 v[14:17], v57 offset:16688
	ds_read_b128 v[6:9], v57 offset:16704
	v_fma_f32 v114, -v192, v49, v114
	v_fma_f32 v114, -v193, v50, v114
	v_fma_f32 v114, -v194, v51, v114
	v_fma_f32 v114, -v195, v52, v114
	v_fma_f32 v114, -v196, v53, v114
	v_fma_f32 v114, -v197, v54, v114
	v_fma_f32 v114, -v198, v55, v114
	v_fma_f32 v114, -v199, v56, v114
	v_fma_f32 v114, -v34, v58, v114
	v_fma_f32 v114, -v35, v59, v114
	v_fma_f32 v114, -v36, v60, v114
	v_fma_f32 v114, -v37, v61, v114
	v_fma_f32 v114, -v26, v64, v114
	v_fma_f32 v114, -v27, v65, v114
	v_fma_f32 v114, -v28, v66, v114
	v_fma_f32 v114, -v29, v67, v114
	v_fma_f32 v114, -v18, v68, v114
	v_fma_f32 v114, -v19, v69, v114
	v_fma_f32 v114, -v20, v70, v114
	v_fma_f32 v114, -v21, v71, v114
	v_fma_f32 v114, -v10, v72, v114
	v_fma_f32 v114, -v11, v73, v114
	v_fma_f32 v114, -v12, v74, v114
	v_fma_f32 v114, -v13, v75, v114
	v_fma_f32 v114, -v2, v76, v114
	v_fma_f32 v114, -v3, v77, v114
	v_fma_f32 v114, -v4, v78, v114
	v_fma_f32 v114, -v5, v79, v114
	v_fma_f32 v114, -v120, v80, v114
	v_fma_f32 v114, -v121, v81, v114
	v_fma_f32 v114, -v122, v82, v114
	v_fma_f32 v114, -v123, v83, v114
	v_fma_f32 v114, -v124, v84, v114
	v_fma_f32 v114, -v125, v85, v114
	v_fma_f32 v114, -v126, v86, v114
	v_fma_f32 v114, -v127, v87, v114
	s_waitcnt lgkmcnt(12)
	v_fma_f32 v114, -v128, v88, v114
	v_fma_f32 v114, -v129, v89, v114
	v_fma_f32 v114, -v130, v90, v114
	v_fma_f32 v114, -v131, v91, v114
	s_waitcnt lgkmcnt(11)
	v_fma_f32 v114, -v132, v92, v114
	v_fma_f32 v114, -v133, v93, v114
	v_fma_f32 v114, -v134, v94, v114
	v_fma_f32 v114, -v135, v95, v114
	s_waitcnt lgkmcnt(10)
	v_fma_f32 v114, -v144, v96, v114
	v_fma_f32 v114, -v145, v97, v114
	v_fma_f32 v114, -v146, v98, v114
	v_fma_f32 v114, -v147, v103, v114
	s_waitcnt lgkmcnt(9)
	v_fma_f32 v114, -v148, v106, v114
	v_fma_f32 v114, -v149, v107, v114
	v_fma_f32 v114, -v150, v108, v114
	v_fma_f32 v114, -v151, v109, v114
	s_waitcnt lgkmcnt(8)
	v_fma_f32 v114, -v152, v110, v114
	v_fma_f32 v114, -v153, v111, v114
	v_fma_f32 v114, -v154, v112, v114
	v_fma_f32 v114, -v155, v113, v114
	s_waitcnt lgkmcnt(7)
	v_fma_f32 v115, -v156, v45, v115
	ds_read_b128 v[120:123], v57 offset:16720
	ds_read_b128 v[124:127], v57 offset:16736
	ds_read_b128 v[128:131], v57 offset:16752
	ds_read_b128 v[132:135], v57 offset:16768
	ds_read_u16 v2, v63 offset:16864
	ds_read_b32 v3, v62 offset:248
	ds_read_b128 v[144:147], v57 offset:16784
	ds_read_b128 v[148:151], v57 offset:16800
	ds_read_b128 v[152:155], v57 offset:16816
	ds_read_b128 v[188:191], v57 offset:16832
	v_fma_f32 v115, -v157, v46, v115
	s_waitcnt lgkmcnt(5)
	v_lshlrev_b32_e32 v2, 16, v2
	v_fma_f32 v115, -v158, v47, v115
	s_waitcnt lgkmcnt(4)
	v_mul_f32_e32 v116, v3, v2
	v_fma_f32 v115, -v159, v48, v115
	s_waitcnt lgkmcnt(0)
	ds_read_b128 v[190:193], v57 offset:16864
	ds_read_b128 v[194:197], v57 offset:16880
	ds_read_b128 v[198:201], v57 offset:16896
	ds_read_b128 v[34:37], v57 offset:16912
	ds_read_b128 v[26:29], v57 offset:16928
	ds_read_b128 v[18:21], v57 offset:16944
	ds_read_b128 v[10:13], v57 offset:16960
	ds_read_b128 v[2:5], v57 offset:16976
	v_fma_f32 v115, -v180, v49, v115
	v_fma_f32 v115, -v181, v50, v115
	v_fma_f32 v115, -v182, v51, v115
	v_fma_f32 v115, -v183, v52, v115
	v_fma_f32 v115, -v184, v53, v115
	v_fma_f32 v115, -v185, v54, v115
	v_fma_f32 v115, -v186, v55, v115
	v_fma_f32 v115, -v187, v56, v115
	v_fma_f32 v115, -v38, v58, v115
	v_fma_f32 v115, -v39, v59, v115
	v_fma_f32 v115, -v40, v60, v115
	v_fma_f32 v115, -v41, v61, v115
	v_fma_f32 v115, -v30, v64, v115
	v_fma_f32 v115, -v31, v65, v115
	v_fma_f32 v115, -v32, v66, v115
	v_fma_f32 v115, -v33, v67, v115
	v_fma_f32 v115, -v22, v68, v115
	v_fma_f32 v115, -v23, v69, v115
	v_fma_f32 v115, -v24, v70, v115
	v_fma_f32 v115, -v25, v71, v115
	v_fma_f32 v115, -v14, v72, v115
	v_fma_f32 v115, -v15, v73, v115
	v_fma_f32 v115, -v16, v74, v115
	v_fma_f32 v115, -v17, v75, v115
	v_fma_f32 v115, -v6, v76, v115
	v_fma_f32 v115, -v7, v77, v115
	v_fma_f32 v115, -v8, v78, v115
	v_fma_f32 v115, -v9, v79, v115
	v_fma_f32 v115, -v120, v80, v115
	v_fma_f32 v115, -v121, v81, v115
	v_fma_f32 v115, -v122, v82, v115
	v_fma_f32 v115, -v123, v83, v115
	v_fma_f32 v115, -v124, v84, v115
	v_fma_f32 v115, -v125, v85, v115
	v_fma_f32 v115, -v126, v86, v115
	v_fma_f32 v115, -v127, v87, v115
	v_fma_f32 v115, -v128, v88, v115
	v_fma_f32 v115, -v129, v89, v115
	v_fma_f32 v115, -v130, v90, v115
	v_fma_f32 v115, -v131, v91, v115
	v_fma_f32 v115, -v132, v92, v115
	v_fma_f32 v115, -v133, v93, v115
	v_fma_f32 v115, -v134, v94, v115
	v_fma_f32 v115, -v135, v95, v115
	v_fma_f32 v115, -v144, v96, v115
	v_fma_f32 v115, -v145, v97, v115
	v_fma_f32 v115, -v146, v98, v115
	v_fma_f32 v115, -v147, v103, v115
	v_fma_f32 v115, -v148, v106, v115
	v_fma_f32 v115, -v149, v107, v115
	v_fma_f32 v115, -v150, v108, v115
	v_fma_f32 v115, -v151, v109, v115
	v_fma_f32 v115, -v152, v110, v115
	v_fma_f32 v115, -v153, v111, v115
	v_fma_f32 v115, -v154, v112, v115
	v_fma_f32 v115, -v155, v113, v115
	v_fma_f32 v115, -v188, v114, v115
	s_waitcnt lgkmcnt(7)
	v_fma_f32 v116, -v190, v45, v116
	ds_read_b128 v[120:123], v57 offset:16992
	ds_read_b128 v[124:127], v57 offset:17008
	ds_read_b128 v[128:131], v57 offset:17024
	ds_read_b128 v[132:135], v57 offset:17040
	ds_read_u16 v6, v63 offset:17136
	ds_read_b32 v7, v62 offset:252
	ds_read_b128 v[144:147], v57 offset:17056
	ds_read_b128 v[148:151], v57 offset:17072
	ds_read_b128 v[152:155], v57 offset:17088
	ds_read_b128 v[156:159], v57 offset:17104
	v_fma_f32 v116, -v191, v46, v116
	s_waitcnt lgkmcnt(5)
	v_lshlrev_b32_e32 v6, 16, v6
	v_fma_f32 v116, -v192, v47, v116
	s_waitcnt lgkmcnt(4)
	v_mul_f32_e32 v38, v7, v6
	v_fma_f32 v116, -v193, v48, v116
	s_waitcnt lgkmcnt(0)
	ds_read_b128 v[158:161], v57 offset:17136
	ds_read_b128 v[180:183], v57 offset:17152
	ds_read_b128 v[184:187], v57 offset:17168
	ds_read_b128 v[202:205], v57 offset:17184
	ds_read_b128 v[30:33], v57 offset:17200
	ds_read_b128 v[22:25], v57 offset:17216
	ds_read_b128 v[14:17], v57 offset:17232
	ds_read_b128 v[6:9], v57 offset:17248
	v_fma_f32 v116, -v194, v49, v116
	v_fma_f32 v116, -v195, v50, v116
	v_fma_f32 v116, -v196, v51, v116
	v_fma_f32 v116, -v197, v52, v116
	v_fma_f32 v116, -v198, v53, v116
	v_fma_f32 v116, -v199, v54, v116
	v_fma_f32 v116, -v200, v55, v116
	v_fma_f32 v116, -v201, v56, v116
	v_fma_f32 v116, -v34, v58, v116
	v_fma_f32 v116, -v35, v59, v116
	v_fma_f32 v116, -v36, v60, v116
	v_fma_f32 v116, -v37, v61, v116
	v_fma_f32 v116, -v26, v64, v116
	v_fma_f32 v116, -v27, v65, v116
	v_fma_f32 v116, -v28, v66, v116
	v_fma_f32 v116, -v29, v67, v116
	v_fma_f32 v116, -v18, v68, v116
	v_fma_f32 v116, -v19, v69, v116
	v_fma_f32 v116, -v20, v70, v116
	v_fma_f32 v116, -v21, v71, v116
	v_fma_f32 v116, -v10, v72, v116
	v_fma_f32 v116, -v11, v73, v116
	v_fma_f32 v116, -v12, v74, v116
	v_fma_f32 v116, -v13, v75, v116
	v_fma_f32 v116, -v2, v76, v116
	v_fma_f32 v116, -v3, v77, v116
	v_fma_f32 v116, -v4, v78, v116
	v_fma_f32 v116, -v5, v79, v116
	v_fma_f32 v116, -v120, v80, v116
	v_fma_f32 v116, -v121, v81, v116
	v_fma_f32 v116, -v122, v82, v116
	v_fma_f32 v116, -v123, v83, v116
	v_fma_f32 v116, -v124, v84, v116
	v_fma_f32 v116, -v125, v85, v116
	v_fma_f32 v116, -v126, v86, v116
	v_fma_f32 v116, -v127, v87, v116
	v_fma_f32 v116, -v128, v88, v116
	v_fma_f32 v116, -v129, v89, v116
	v_fma_f32 v116, -v130, v90, v116
	v_fma_f32 v116, -v131, v91, v116
	v_fma_f32 v116, -v132, v92, v116
	v_fma_f32 v116, -v133, v93, v116
	v_fma_f32 v116, -v134, v94, v116
	v_fma_f32 v116, -v135, v95, v116
	v_fma_f32 v116, -v144, v96, v116
	v_fma_f32 v116, -v145, v97, v116
	v_fma_f32 v116, -v146, v98, v116
	v_fma_f32 v116, -v147, v103, v116
	v_fma_f32 v116, -v148, v106, v116
	v_fma_f32 v116, -v149, v107, v116
	v_fma_f32 v116, -v150, v108, v116
	v_fma_f32 v116, -v151, v109, v116
	v_fma_f32 v116, -v152, v110, v116
	v_fma_f32 v116, -v153, v111, v116
	v_fma_f32 v116, -v154, v112, v116
	v_fma_f32 v116, -v155, v113, v116
	v_fma_f32 v116, -v156, v114, v116
	v_fma_f32 v116, -v157, v115, v116
	s_waitcnt lgkmcnt(7)
	v_fma_f32 v38, -v158, v45, v38
	ds_read_b128 v[2:5], v57 offset:17264
	ds_read_b128 v[10:13], v57 offset:17280
	ds_read_b128 v[18:21], v57 offset:17296
	ds_read_b128 v[26:29], v57 offset:17312
	ds_read_b128 v[34:37], v57 offset:17328
	ds_read_b128 v[120:123], v57 offset:17344
	ds_read_b128 v[124:127], v57 offset:17360
	ds_read_b128 v[128:131], v57 offset:17376
	v_fma_f32 v38, -v159, v46, v38
	s_waitcnt lgkmcnt(0)
	v_fma_f32 v38, -v160, v47, v38
	v_fma_f32 v38, -v161, v48, v38
	v_fma_f32 v38, -v180, v49, v38
	v_fma_f32 v38, -v181, v50, v38
	v_fma_f32 v38, -v182, v51, v38
	v_fma_f32 v38, -v183, v52, v38
	v_fma_f32 v38, -v184, v53, v38
	v_fma_f32 v38, -v185, v54, v38
	v_fma_f32 v38, -v186, v55, v38
	v_fma_f32 v38, -v187, v56, v38
	v_fma_f32 v38, -v202, v58, v38
	v_fma_f32 v38, -v203, v59, v38
	v_fma_f32 v38, -v204, v60, v38
	v_fma_f32 v38, -v205, v61, v38
	v_fma_f32 v38, -v30, v64, v38
	v_fma_f32 v38, -v31, v65, v38
	v_fma_f32 v38, -v32, v66, v38
	v_fma_f32 v38, -v33, v67, v38
	v_fma_f32 v38, -v22, v68, v38
	v_fma_f32 v38, -v23, v69, v38
	v_fma_f32 v38, -v24, v70, v38
	v_fma_f32 v38, -v25, v71, v38
	v_fma_f32 v38, -v14, v72, v38
	v_fma_f32 v38, -v15, v73, v38
	v_fma_f32 v38, -v16, v74, v38
	v_fma_f32 v38, -v17, v75, v38
	v_fma_f32 v38, -v6, v76, v38
	v_fma_f32 v38, -v7, v77, v38
	v_fma_f32 v38, -v8, v78, v38
	v_fma_f32 v38, -v9, v79, v38
	v_fma_f32 v38, -v2, v80, v38
	v_fma_f32 v38, -v3, v81, v38
	v_fma_f32 v38, -v4, v82, v38
	v_fma_f32 v38, -v5, v83, v38
	v_fma_f32 v38, -v10, v84, v38
	v_fma_f32 v38, -v11, v85, v38
	v_fma_f32 v38, -v12, v86, v38
	v_fma_f32 v38, -v13, v87, v38
	v_fma_f32 v38, -v18, v88, v38
	v_fma_f32 v38, -v19, v89, v38
	v_fma_f32 v38, -v20, v90, v38
	v_fma_f32 v38, -v21, v91, v38
	v_fma_f32 v38, -v26, v92, v38
	v_fma_f32 v38, -v27, v93, v38
	v_fma_f32 v38, -v28, v94, v38
	v_fma_f32 v38, -v29, v95, v38
	v_fma_f32 v38, -v34, v96, v38
	v_fma_f32 v38, -v35, v97, v38
	v_fma_f32 v38, -v36, v98, v38
	v_fma_f32 v38, -v37, v103, v38
	v_fma_f32 v38, -v120, v106, v38
	v_fma_f32 v38, -v121, v107, v38
	v_fma_f32 v38, -v122, v108, v38
	v_fma_f32 v38, -v123, v109, v38
	v_fma_f32 v38, -v124, v110, v38
	v_fma_f32 v38, -v125, v111, v38
	v_fma_f32 v38, -v126, v112, v38
	v_fma_f32 v38, -v127, v113, v38
	v_fma_f32 v38, -v128, v114, v38
	v_fma_f32 v38, -v129, v115, v38
	v_fma_f32 v38, -v130, v116, v38
	s_and_saveexec_b64 s[56:57], s[4:5]
	ds_add_u32 v169, v170 offset:36352
	s_or_b64 exec, exec, s[56:57]
	ds_read_b32 v2, v169 offset:36352
	s_add_i32 s7, s3, 16
	s_waitcnt lgkmcnt(0)
	v_cmp_gt_u32_e32 vcc, s7, v2
	s_and_saveexec_b64 s[56:57], vcc
	s_cbranch_execz .LBB0_519
	s_mov_b64 s[58:59], 0
